# single-tile GEMM K loops: skip useless next-tile prefetch DMAs in the last K iteration (counted waits re-derived)
# baseline (speedup 1.0000x reference)
; #define PG8_STAGE(bufoff, gbase, voff) do { _Pragma("unroll") for (int _i = 0; _i < 2; ++_i) \
;         __builtin_amdgcn_global_load_lds((const unsigned*)((const char*)(gbase) + (voff)[_i]), (LAS unsigned*)(lds + (bufoff) + ldsw + _i * 8192), 16, 0, 0); } while (0)
; #define PG8_LDA(dst, b, h) do { _Pragma("unroll") for (int m = 0; m < 4; ++m) _Pragma("unroll") for (int k = 0; k < 2; ++k) dst[m][k] = *(const LAS bf16x8*)(lds + PG8_SA(b, h) + aoff + m * 2048 + k * 1024); } while (0)
; #define PG8_LDB(dst, b, h) do { _Pragma("unroll") for (int n = 0; n < 2; ++n) _Pragma("unroll") for (int k = 0; k < 2; ++k) dst[n][k] = *(const LAS bf16x8*)(lds + PG8_SB(b, h) + boff + n * 2048 + k * 1024); } while (0)
; #define PG8_MMA(ai, bj, At, Bt) do { __builtin_amdgcn_s_setprio(1); _Pragma("unroll") for (int m = 0; m < 4; ++m) _Pragma("unroll") for (int n = 0; n < 2; ++n) _Pragma("unroll") for (int k = 0; k < 2; ++k) \
;         acc[ai][bj][m][n] = __builtin_amdgcn_mfma_f32_16x16x32_bf16(Bt[n][k], At[m][k], acc[ai][bj][m][n], 0, 0, 0); __builtin_amdgcn_s_setprio(0); } while (0)
; #define PG8_WAIT_V(n) asm volatile("s_waitcnt vmcnt(" #n ")" ::: "memory")
; #define PG8_BAR __builtin_amdgcn_s_barrier()
; template <class Epi, class Sched, bool ALIGN_EPI = GEMM_ALIGN, bool SP2 = GEMM_SP2>
; __device__ __forceinline__ void gemm_phase(lptr lds, const Gemm g, const Sched& S, const Epi& E) {
;     ...
;         const char* nA = has_next ? (const char*)g.A + (size_t)nxt.pm * tstepA + (size_t)nxt.acol * 2 : cA; const char* nB = has_next ? (const char*)g.Bt + (size_t)nxt.pn * tstepB : cB;
;         for (int t = 0; t < nt; t += 2) {
;             const bool last = (t == nt - 2);
;             const char* a1 = cA + (size_t)(t + 1) * kstep;
;             const char* a2 = last ? nA : cA + (size_t)(t + 2) * kstep; const char* b2 = last ? nB : cB + (size_t)(t + 2) * kstep;
;             const char* a3 = a2 + kstep; const char* b3 = b2 + kstep;
;             if constexpr (SP2) {
;             PG8_LDB(B0, 0, 0); PG8_LDB(B1, 0, 1); PG8_SCHED; PG8_LDA(At, 0, 0); PG8_STAGE(PG8_SA(1, 1), a1 + hstepA, voffA);
;             PG8_WAIT_V(8); PG8_WAIT_L(0); PG8_BAR; PG8_MMA(0, 0, At, B0); PG8_MMA(0, 1, At, B1); PG8_BAR; PG8_SCHED;
;             PG8_LDA(At, 0, 1); PG8_STAGE(PG8_SB(0, 0), b2, voffB); PG8_STAGE(PG8_SB(0, 1), b2 + hstepB, voffB); PG8_STAGE(PG8_SA(0, 0), a2, voffA);
.LBB0_313:
	s_add_u32 s28, s24, 0x100
	s_addc_u32 s29, s25, 0
	s_add_i32 s67, 0, 0x10000
	s_cmp_eq_u32 s66, 40
	s_cselect_b32 s100, 1, 0
	s_cselect_b32 s47, s3, s29
	s_cselect_b32 s46, s2, s28
	s_cselect_b32 s31, s45, s65
	s_cselect_b32 s30, s44, s64
	s_add_i32 s68, 0, 0x14000
	v_add_u32_e32 v62, s67, v177
	v_add_u32_e32 v158, s68, v177
	ds_read_b128 v[50:53], v62
	ds_read_b128 v[54:57], v62 offset:1024
	ds_read_b128 v[58:61], v62 offset:2048
	ds_read_b128 v[62:65], v62 offset:3072
	ds_read_b128 v[146:149], v158
	ds_read_b128 v[150:153], v158 offset:1024
	ds_read_b128 v[154:157], v158 offset:2048
	ds_read_b128 v[158:161], v158 offset:3072
	v_lshl_add_u64 v[214:215], s[24:25], 0, v[164:165]
	s_add_i32 m0, s51, 0xc000
	ds_read_b128 v[168:171], v179
	ds_read_b128 v[172:175], v179 offset:1024
	ds_read_b128 v[180:183], v179 offset:2048
	ds_read_b128 v[198:201], v179 offset:3072
	ds_read_b128 v[202:205], v179 offset:4096
	ds_read_b128 v[206:209], v179 offset:5120
	ds_read_b128 v[210:213], v179 offset:6144
	ds_read_b128 v[220:223], v179 offset:7168
	global_load_lds_dwordx4 v[214:215], off
	v_lshl_add_u64 v[214:215], s[24:25], 0, v[166:167]
	s_add_i32 m0, s51, 0xe000
	s_nop 0
	global_load_lds_dwordx4 v[214:215], off
	s_waitcnt vmcnt(8)
	s_waitcnt lgkmcnt(0)
	s_barrier
	s_setprio 1
	s_waitcnt lgkmcnt(0)
	v_mfma_f32_16x16x32_bf16 v[142:145], v[50:53], v[168:171], v[142:145]
	v_mfma_f32_16x16x32_bf16 v[138:141], v[58:61], v[168:171], v[138:141]
	v_mfma_f32_16x16x32_bf16 v[126:129], v[50:53], v[180:183], v[126:129]
	v_mfma_f32_16x16x32_bf16 v[122:125], v[58:61], v[180:183], v[122:125]
	v_mfma_f32_16x16x32_bf16 v[110:113], v[50:53], v[202:205], v[110:113]
	v_mfma_f32_16x16x32_bf16 v[106:109], v[58:61], v[202:205], v[106:109]
	v_mfma_f32_16x16x32_bf16 v[94:97], v[50:53], v[210:213], v[94:97]
	v_mfma_f32_16x16x32_bf16 v[90:93], v[58:61], v[210:213], v[90:93]
	v_mfma_f32_16x16x32_bf16 v[142:145], v[54:57], v[172:175], v[142:145]
	v_mfma_f32_16x16x32_bf16 v[138:141], v[62:65], v[172:175], v[138:141]
	v_mfma_f32_16x16x32_bf16 v[126:129], v[54:57], v[198:201], v[126:129]
	v_mfma_f32_16x16x32_bf16 v[122:125], v[62:65], v[198:201], v[122:125]
	v_mfma_f32_16x16x32_bf16 v[110:113], v[54:57], v[206:209], v[110:113]
	v_mfma_f32_16x16x32_bf16 v[106:109], v[62:65], v[206:209], v[106:109]
	v_mfma_f32_16x16x32_bf16 v[94:97], v[54:57], v[220:223], v[94:97]
	v_mfma_f32_16x16x32_bf16 v[90:93], v[62:65], v[220:223], v[90:93]
	s_setprio 0
	s_setprio 1
	v_mfma_f32_16x16x32_bf16 v[134:137], v[146:149], v[168:171], v[134:137]
	v_mfma_f32_16x16x32_bf16 v[130:133], v[154:157], v[168:171], v[130:133]
	v_mfma_f32_16x16x32_bf16 v[118:121], v[146:149], v[180:183], v[118:121]
	v_mfma_f32_16x16x32_bf16 v[114:117], v[154:157], v[180:183], v[114:117]
	v_mfma_f32_16x16x32_bf16 v[102:105], v[146:149], v[202:205], v[102:105]
	v_mfma_f32_16x16x32_bf16 v[98:101], v[154:157], v[202:205], v[98:101]
	v_mfma_f32_16x16x32_bf16 v[86:89], v[146:149], v[210:213], v[86:89]
	v_mfma_f32_16x16x32_bf16 v[82:85], v[154:157], v[210:213], v[82:85]
	v_mfma_f32_16x16x32_bf16 v[134:137], v[150:153], v[172:175], v[134:137]
	v_mfma_f32_16x16x32_bf16 v[130:133], v[158:161], v[172:175], v[130:133]
	v_mfma_f32_16x16x32_bf16 v[118:121], v[150:153], v[198:201], v[118:121]
	v_mfma_f32_16x16x32_bf16 v[114:117], v[158:161], v[198:201], v[114:117]
	v_mfma_f32_16x16x32_bf16 v[102:105], v[150:153], v[206:209], v[102:105]
	v_mfma_f32_16x16x32_bf16 v[98:101], v[158:161], v[206:209], v[98:101]
	v_mfma_f32_16x16x32_bf16 v[86:89], v[150:153], v[220:223], v[86:89]
	v_mfma_f32_16x16x32_bf16 v[82:85], v[158:161], v[220:223], v[82:85]
	s_setprio 0
	s_barrier
	s_cmp_lg_u32 s100, 0
	s_cbranch_scc1 .Lmy_fo313_p1
	s_add_i32 s24, s67, s50
	v_lshl_add_u64 v[214:215], s[30:31], 0, v[0:1]
	s_mov_b32 m0, s24
	ds_read_b128 v[168:171], v179 offset:16384
	ds_read_b128 v[172:175], v179 offset:17408
	ds_read_b128 v[180:183], v179 offset:18432
	ds_read_b128 v[198:201], v179 offset:19456
	ds_read_b128 v[202:205], v179 offset:20480
	ds_read_b128 v[206:209], v179 offset:21504
	ds_read_b128 v[210:213], v179 offset:22528
	ds_read_b128 v[220:223], v179 offset:23552
	global_load_lds_dwordx4 v[214:215], off
	s_add_i32 m0, s24, 0x2000
	s_add_u32 s24, s30, 0xb0000
	v_lshl_add_u64 v[224:225], s[30:31], 0, v[162:163]
	s_addc_u32 s25, s31, 0
	s_add_i32 s67, s68, s50
	global_load_lds_dwordx4 v[224:225], off
	v_lshl_add_u64 v[226:227], s[24:25], 0, v[0:1]
	s_mov_b32 m0, s67
	v_lshl_add_u64 v[228:229], s[46:47], 0, v[162:163]
	global_load_lds_dwordx4 v[226:227], off
	v_lshl_add_u64 v[226:227], s[24:25], 0, v[162:163]
	s_add_i32 m0, s67, 0x2000
	s_nop 0
	global_load_lds_dwordx4 v[226:227], off
	v_lshl_add_u64 v[226:227], s[46:47], 0, v[0:1]
	s_mov_b32 m0, s51
	s_nop 0
	global_load_lds_dwordx4 v[226:227], off
	s_mov_b32 m0, s52
	s_nop 0
	global_load_lds_dwordx4 v[228:229], off
	s_waitcnt vmcnt(8)
; #define PG8_STAGE(bufoff, gbase, voff) do { _Pragma("unroll") for (int _i = 0; _i < 2; ++_i) \
;         __builtin_amdgcn_global_load_lds((const unsigned*)((const char*)(gbase) + (voff)[_i]), (LAS unsigned*)(lds + (bufoff) + ldsw + _i * 8192), 16, 0, 0); } while (0)
; #define PG8_LDA(dst, b, h) do { _Pragma("unroll") for (int m = 0; m < 4; ++m) _Pragma("unroll") for (int k = 0; k < 2; ++k) dst[m][k] = *(const LAS bf16x8*)(lds + PG8_SA(b, h) + aoff + m * 2048 + k * 1024); } while (0)
; #define PG8_LDB(dst, b, h) do { _Pragma("unroll") for (int n = 0; n < 2; ++n) _Pragma("unroll") for (int k = 0; k < 2; ++k) dst[n][k] = *(const LAS bf16x8*)(lds + PG8_SB(b, h) + boff + n * 2048 + k * 1024); } while (0)
; #define PG8_MMA(ai, bj, At, Bt) do { __builtin_amdgcn_s_setprio(1); _Pragma("unroll") for (int m = 0; m < 4; ++m) _Pragma("unroll") for (int n = 0; n < 2; ++n) _Pragma("unroll") for (int k = 0; k < 2; ++k) \
;         acc[ai][bj][m][n] = __builtin_amdgcn_mfma_f32_16x16x32_bf16(Bt[n][k], At[m][k], acc[ai][bj][m][n], 0, 0, 0); __builtin_amdgcn_s_setprio(0); } while (0)
; #define PG8_WAIT_V(n) asm volatile("s_waitcnt vmcnt(" #n ")" ::: "memory")
; #define PG8_WAIT_L(n) asm volatile("s_waitcnt lgkmcnt(" #n ")" ::: "memory")
; #define PG8_BAR __builtin_amdgcn_s_barrier()
; #define PG8_SCHED __builtin_amdgcn_sched_barrier(0)
; template <class Epi, class Sched, bool ALIGN_EPI = GEMM_ALIGN, bool SP2 = GEMM_SP2>
; __device__ __forceinline__ void gemm_phase(lptr lds, const Gemm g, const Sched& S, const Epi& E) {
;     ...
;             PG8_WAIT_V(8); PG8_WAIT_L(0); PG8_BAR; PG8_MMA(0, 0, At, B0); PG8_MMA(0, 1, At, B1); PG8_BAR; PG8_SCHED;
;             PG8_LDA(At, 0, 1); PG8_STAGE(PG8_SB(0, 0), b2, voffB); PG8_STAGE(PG8_SB(0, 1), b2 + hstepB, voffB); PG8_STAGE(PG8_SA(0, 0), a2, voffA);
;             PG8_WAIT_V(8); PG8_WAIT_L(0); PG8_BAR; PG8_MMA(1, 0, At, B0); PG8_MMA(1, 1, At, B1); PG8_BAR; PG8_SCHED;
;             PG8_LDB(B0, 1, 0); PG8_LDB(B1, 1, 1); PG8_SCHED; PG8_LDA(At, 1, 0); PG8_STAGE(PG8_SA(0, 1), a2 + hstepA, voffA);
;             PG8_WAIT_V(8); PG8_WAIT_L(0); PG8_BAR; PG8_MMA(0, 0, At, B0); PG8_MMA(0, 1, At, B1); PG8_BAR; PG8_SCHED;
;             PG8_LDA(At, 1, 1); PG8_STAGE(PG8_SB(1, 0), b3, voffB); PG8_STAGE(PG8_SB(1, 1), b3 + hstepB, voffB); PG8_STAGE(PG8_SA(1, 0), a3, voffA);
.Lmy_fo313_j1:
	s_waitcnt lgkmcnt(0)
	s_barrier
	s_setprio 1
	s_waitcnt lgkmcnt(0)
	v_mfma_f32_16x16x32_bf16 v[78:81], v[50:53], v[168:171], v[78:81]
	v_mfma_f32_16x16x32_bf16 v[74:77], v[58:61], v[168:171], v[74:77]
	v_mfma_f32_16x16x32_bf16 v[46:49], v[50:53], v[180:183], v[46:49]
	v_mfma_f32_16x16x32_bf16 v[42:45], v[58:61], v[180:183], v[42:45]
	v_mfma_f32_16x16x32_bf16 v[30:33], v[50:53], v[202:205], v[30:33]
	v_mfma_f32_16x16x32_bf16 v[26:29], v[58:61], v[202:205], v[26:29]
	v_mfma_f32_16x16x32_bf16 v[14:17], v[50:53], v[210:213], v[14:17]
	v_mfma_f32_16x16x32_bf16 v[10:13], v[58:61], v[210:213], v[10:13]
	v_mfma_f32_16x16x32_bf16 v[78:81], v[54:57], v[172:175], v[78:81]
	v_mfma_f32_16x16x32_bf16 v[74:77], v[62:65], v[172:175], v[74:77]
	v_mfma_f32_16x16x32_bf16 v[46:49], v[54:57], v[198:201], v[46:49]
	v_mfma_f32_16x16x32_bf16 v[42:45], v[62:65], v[198:201], v[42:45]
	v_mfma_f32_16x16x32_bf16 v[30:33], v[54:57], v[206:209], v[30:33]
	v_mfma_f32_16x16x32_bf16 v[26:29], v[62:65], v[206:209], v[26:29]
	v_mfma_f32_16x16x32_bf16 v[14:17], v[54:57], v[220:223], v[14:17]
	v_mfma_f32_16x16x32_bf16 v[10:13], v[62:65], v[220:223], v[10:13]
	s_setprio 0
	s_setprio 1
	v_mfma_f32_16x16x32_bf16 v[38:41], v[146:149], v[180:183], v[38:41]
	v_mfma_f32_16x16x32_bf16 v[34:37], v[154:157], v[180:183], v[34:37]
	v_mfma_f32_16x16x32_bf16 v[22:25], v[146:149], v[202:205], v[22:25]
	v_mfma_f32_16x16x32_bf16 v[18:21], v[154:157], v[202:205], v[18:21]
	v_mfma_f32_16x16x32_bf16 v[6:9], v[146:149], v[210:213], v[6:9]
	v_mfma_f32_16x16x32_bf16 v[2:5], v[154:157], v[210:213], v[2:5]
	v_mfma_f32_16x16x32_bf16 v[50:53], v[146:149], v[168:171], v[70:73]
	v_mfma_f32_16x16x32_bf16 v[54:57], v[154:157], v[168:171], v[66:69]
	v_mfma_f32_16x16x32_bf16 v[38:41], v[150:153], v[198:201], v[38:41]
	v_mfma_f32_16x16x32_bf16 v[34:37], v[158:161], v[198:201], v[34:37]
	v_mfma_f32_16x16x32_bf16 v[22:25], v[150:153], v[206:209], v[22:25]
	v_mfma_f32_16x16x32_bf16 v[18:21], v[158:161], v[206:209], v[18:21]
	v_mfma_f32_16x16x32_bf16 v[6:9], v[150:153], v[220:223], v[6:9]
	v_mfma_f32_16x16x32_bf16 v[2:5], v[158:161], v[220:223], v[2:5]
	v_mfma_f32_16x16x32_bf16 v[50:53], v[150:153], v[172:175], v[50:53]
	v_mfma_f32_16x16x32_bf16 v[54:57], v[158:161], v[172:175], v[54:57]
	s_setprio 0
	s_barrier
	s_cmp_lg_u32 s100, 0
	s_cbranch_scc1 .Lmy_fo313_p2
	s_add_i32 s67, 0, 0x18000
	s_add_i32 s68, 0, 0x1c000
	v_add_u32_e32 v70, s67, v177
	v_add_u32_e32 v158, s68, v177
	ds_read_b128 v[58:61], v70
	ds_read_b128 v[62:65], v70 offset:1024
	ds_read_b128 v[66:69], v70 offset:2048
	ds_read_b128 v[70:73], v70 offset:3072
	ds_read_b128 v[146:149], v158
	ds_read_b128 v[150:153], v158 offset:1024
	ds_read_b128 v[154:157], v158 offset:2048
	ds_read_b128 v[158:161], v158 offset:3072
	s_add_u32 s24, s46, 0xb0000
	s_addc_u32 s25, s47, 0
	s_mov_b32 m0, s53
	v_lshl_add_u64 v[230:231], s[24:25], 0, v[0:1]
	ds_read_b128 v[168:171], v179 offset:32768
	ds_read_b128 v[172:175], v179 offset:33792
	ds_read_b128 v[180:183], v179 offset:34816
	ds_read_b128 v[198:201], v179 offset:35840
	ds_read_b128 v[202:205], v179 offset:36864
	ds_read_b128 v[206:209], v179 offset:37888
	ds_read_b128 v[210:213], v179 offset:38912
	ds_read_b128 v[220:223], v179 offset:39936
	global_load_lds_dwordx4 v[230:231], off
	v_lshl_add_u64 v[230:231], s[24:25], 0, v[162:163]
	s_mov_b32 m0, s54
	s_nop 0
	global_load_lds_dwordx4 v[230:231], off
	s_waitcnt vmcnt(8)
.Lmy_fo313_j2:
	s_waitcnt lgkmcnt(0)
	s_barrier
	s_setprio 1
	s_waitcnt lgkmcnt(0)
	v_mfma_f32_16x16x32_bf16 v[142:145], v[58:61], v[168:171], v[142:145]
	v_mfma_f32_16x16x32_bf16 v[138:141], v[66:69], v[168:171], v[138:141]
	v_mfma_f32_16x16x32_bf16 v[126:129], v[58:61], v[180:183], v[126:129]
	v_mfma_f32_16x16x32_bf16 v[122:125], v[66:69], v[180:183], v[122:125]
	v_mfma_f32_16x16x32_bf16 v[110:113], v[58:61], v[202:205], v[110:113]
	v_mfma_f32_16x16x32_bf16 v[106:109], v[66:69], v[202:205], v[106:109]
	v_mfma_f32_16x16x32_bf16 v[94:97], v[58:61], v[210:213], v[94:97]
	v_mfma_f32_16x16x32_bf16 v[90:93], v[66:69], v[210:213], v[90:93]
	v_mfma_f32_16x16x32_bf16 v[142:145], v[62:65], v[172:175], v[142:145]
	v_mfma_f32_16x16x32_bf16 v[138:141], v[70:73], v[172:175], v[138:141]
	v_mfma_f32_16x16x32_bf16 v[126:129], v[62:65], v[198:201], v[126:129]
	v_mfma_f32_16x16x32_bf16 v[122:125], v[70:73], v[198:201], v[122:125]
	v_mfma_f32_16x16x32_bf16 v[110:113], v[62:65], v[206:209], v[110:113]
	v_mfma_f32_16x16x32_bf16 v[106:109], v[70:73], v[206:209], v[106:109]
	v_mfma_f32_16x16x32_bf16 v[94:97], v[62:65], v[220:223], v[94:97]
	v_mfma_f32_16x16x32_bf16 v[90:93], v[70:73], v[220:223], v[90:93]
	s_setprio 0
	s_setprio 1
	v_mfma_f32_16x16x32_bf16 v[134:137], v[146:149], v[168:171], v[134:137]
	v_mfma_f32_16x16x32_bf16 v[130:133], v[154:157], v[168:171], v[130:133]
	v_mfma_f32_16x16x32_bf16 v[118:121], v[146:149], v[180:183], v[118:121]
	v_mfma_f32_16x16x32_bf16 v[114:117], v[154:157], v[180:183], v[114:117]
	v_mfma_f32_16x16x32_bf16 v[102:105], v[146:149], v[202:205], v[102:105]
	v_mfma_f32_16x16x32_bf16 v[98:101], v[154:157], v[202:205], v[98:101]
	v_mfma_f32_16x16x32_bf16 v[86:89], v[146:149], v[210:213], v[86:89]
	v_mfma_f32_16x16x32_bf16 v[82:85], v[154:157], v[210:213], v[82:85]
	v_mfma_f32_16x16x32_bf16 v[134:137], v[150:153], v[172:175], v[134:137]
	v_mfma_f32_16x16x32_bf16 v[130:133], v[158:161], v[172:175], v[130:133]
	v_mfma_f32_16x16x32_bf16 v[118:121], v[150:153], v[198:201], v[118:121]
	v_mfma_f32_16x16x32_bf16 v[114:117], v[158:161], v[198:201], v[114:117]
	v_mfma_f32_16x16x32_bf16 v[102:105], v[150:153], v[206:209], v[102:105]
	v_mfma_f32_16x16x32_bf16 v[98:101], v[158:161], v[206:209], v[98:101]
	v_mfma_f32_16x16x32_bf16 v[86:89], v[150:153], v[220:223], v[86:89]
	v_mfma_f32_16x16x32_bf16 v[82:85], v[158:161], v[220:223], v[82:85]
	s_setprio 0
	s_barrier
; #define PG8_STAGE(bufoff, gbase, voff) do { _Pragma("unroll") for (int _i = 0; _i < 2; ++_i) \
;         __builtin_amdgcn_global_load_lds((const unsigned*)((const char*)(gbase) + (voff)[_i]), (LAS unsigned*)(lds + (bufoff) + ldsw + _i * 8192), 16, 0, 0); } while (0)
; #define PG8_LDA(dst, b, h) do { _Pragma("unroll") for (int m = 0; m < 4; ++m) _Pragma("unroll") for (int k = 0; k < 2; ++k) dst[m][k] = *(const LAS bf16x8*)(lds + PG8_SA(b, h) + aoff + m * 2048 + k * 1024); } while (0)
; #define PG8_LDB(dst, b, h) do { _Pragma("unroll") for (int n = 0; n < 2; ++n) _Pragma("unroll") for (int k = 0; k < 2; ++k) dst[n][k] = *(const LAS bf16x8*)(lds + PG8_SB(b, h) + boff + n * 2048 + k * 1024); } while (0)
; #define PG8_MMA(ai, bj, At, Bt) do { __builtin_amdgcn_s_setprio(1); _Pragma("unroll") for (int m = 0; m < 4; ++m) _Pragma("unroll") for (int n = 0; n < 2; ++n) _Pragma("unroll") for (int k = 0; k < 2; ++k) \
;         acc[ai][bj][m][n] = __builtin_amdgcn_mfma_f32_16x16x32_bf16(Bt[n][k], At[m][k], acc[ai][bj][m][n], 0, 0, 0); __builtin_amdgcn_s_setprio(0); } while (0)
; #define PG8_WAIT_V(n) asm volatile("s_waitcnt vmcnt(" #n ")" ::: "memory")
; #define PG8_WAIT_L(n) asm volatile("s_waitcnt lgkmcnt(" #n ")" ::: "memory")
; #define PG8_BAR __builtin_amdgcn_s_barrier()
; #define PG8_SCHED __builtin_amdgcn_sched_barrier(0)
; template <class Epi, class Sched, bool ALIGN_EPI = GEMM_ALIGN, bool SP2 = GEMM_SP2>
; __device__ __forceinline__ void gemm_phase(lptr lds, const Gemm g, const Sched& S, const Epi& E) {
;     ...
;             PG8_LDB(B0, 1, 0); PG8_LDB(B1, 1, 1); PG8_SCHED; PG8_LDA(At, 1, 0); PG8_STAGE(PG8_SA(0, 1), a2 + hstepA, voffA);
;             PG8_WAIT_V(8); PG8_WAIT_L(0); PG8_BAR; PG8_MMA(0, 0, At, B0); PG8_MMA(0, 1, At, B1); PG8_BAR; PG8_SCHED;
;             PG8_LDA(At, 1, 1); PG8_STAGE(PG8_SB(1, 0), b3, voffB); PG8_STAGE(PG8_SB(1, 1), b3 + hstepB, voffB); PG8_STAGE(PG8_SA(1, 0), a3, voffA);
;             PG8_WAIT_V(8); PG8_WAIT_L(0); PG8_BAR; PG8_MMA(1, 0, At, B0); PG8_MMA(1, 1, At, B1); PG8_BAR; PG8_SCHED;
	s_cmp_lg_u32 s100, 0
	s_cbranch_scc1 .Lmy_fo313_p3
	s_add_i32 s24, s67, s50
	v_lshl_add_u64 v[214:215], v[214:215], 0, s[6:7]
	s_mov_b32 m0, s24
	ds_read_b128 v[168:171], v179 offset:49152
	ds_read_b128 v[172:175], v179 offset:50176
	ds_read_b128 v[180:183], v179 offset:51200
	ds_read_b128 v[198:201], v179 offset:52224
	ds_read_b128 v[202:205], v179 offset:53248
	ds_read_b128 v[206:209], v179 offset:54272
	ds_read_b128 v[210:213], v179 offset:55296
	ds_read_b128 v[220:223], v179 offset:56320
	global_load_lds_dwordx4 v[214:215], off
	s_add_i32 m0, s24, 0x2000
	s_add_u32 s24, s30, 0xb0080
	v_lshl_add_u64 v[214:215], v[224:225], 0, s[6:7]
	s_addc_u32 s25, s31, 0
	s_add_i32 s30, s68, s50
	global_load_lds_dwordx4 v[214:215], off
	v_lshl_add_u64 v[214:215], s[24:25], 0, v[0:1]
	s_mov_b32 m0, s30
	s_nop 0
	global_load_lds_dwordx4 v[214:215], off
	v_lshl_add_u64 v[214:215], s[24:25], 0, v[162:163]
	s_add_i32 m0, s30, 0x2000
	s_nop 0
	global_load_lds_dwordx4 v[214:215], off
	v_lshl_add_u64 v[214:215], v[226:227], 0, s[6:7]
	s_mov_b32 m0, s56
	s_nop 0
	global_load_lds_dwordx4 v[214:215], off
	v_lshl_add_u64 v[214:215], v[228:229], 0, s[6:7]
	s_mov_b32 m0, s57
	s_nop 0
	global_load_lds_dwordx4 v[214:215], off
	s_waitcnt vmcnt(8)
.Lmy_fo313_j3:
	s_waitcnt lgkmcnt(0)
	s_barrier
	s_setprio 1
	s_waitcnt lgkmcnt(0)
	v_mfma_f32_16x16x32_bf16 v[78:81], v[58:61], v[168:171], v[78:81]
	v_mfma_f32_16x16x32_bf16 v[74:77], v[66:69], v[168:171], v[74:77]
	v_mfma_f32_16x16x32_bf16 v[46:49], v[58:61], v[180:183], v[46:49]
	v_mfma_f32_16x16x32_bf16 v[42:45], v[66:69], v[180:183], v[42:45]
	v_mfma_f32_16x16x32_bf16 v[30:33], v[58:61], v[202:205], v[30:33]
	v_mfma_f32_16x16x32_bf16 v[26:29], v[66:69], v[202:205], v[26:29]
	v_mfma_f32_16x16x32_bf16 v[14:17], v[58:61], v[210:213], v[14:17]
	v_mfma_f32_16x16x32_bf16 v[10:13], v[66:69], v[210:213], v[10:13]
	v_mfma_f32_16x16x32_bf16 v[78:81], v[62:65], v[172:175], v[78:81]
	v_mfma_f32_16x16x32_bf16 v[74:77], v[70:73], v[172:175], v[74:77]
	v_mfma_f32_16x16x32_bf16 v[46:49], v[62:65], v[198:201], v[46:49]
	v_mfma_f32_16x16x32_bf16 v[42:45], v[70:73], v[198:201], v[42:45]
	v_mfma_f32_16x16x32_bf16 v[30:33], v[62:65], v[206:209], v[30:33]
	v_mfma_f32_16x16x32_bf16 v[26:29], v[70:73], v[206:209], v[26:29]
	v_mfma_f32_16x16x32_bf16 v[14:17], v[62:65], v[220:223], v[14:17]
	v_mfma_f32_16x16x32_bf16 v[10:13], v[70:73], v[220:223], v[10:13]
	s_setprio 0
	s_setprio 1
	v_mfma_f32_16x16x32_bf16 v[50:53], v[146:149], v[168:171], v[50:53]
	v_mfma_f32_16x16x32_bf16 v[70:73], v[150:153], v[172:175], v[50:53]
	v_mfma_f32_16x16x32_bf16 v[50:53], v[154:157], v[168:171], v[54:57]
	v_mfma_f32_16x16x32_bf16 v[38:41], v[146:149], v[180:183], v[38:41]
	v_mfma_f32_16x16x32_bf16 v[34:37], v[154:157], v[180:183], v[34:37]
	v_mfma_f32_16x16x32_bf16 v[22:25], v[146:149], v[202:205], v[22:25]
	v_mfma_f32_16x16x32_bf16 v[18:21], v[154:157], v[202:205], v[18:21]
	v_mfma_f32_16x16x32_bf16 v[6:9], v[146:149], v[210:213], v[6:9]
	v_mfma_f32_16x16x32_bf16 v[2:5], v[154:157], v[210:213], v[2:5]
	v_mfma_f32_16x16x32_bf16 v[66:69], v[158:161], v[172:175], v[50:53]
	v_mfma_f32_16x16x32_bf16 v[38:41], v[150:153], v[198:201], v[38:41]
	v_mfma_f32_16x16x32_bf16 v[34:37], v[158:161], v[198:201], v[34:37]
	v_mfma_f32_16x16x32_bf16 v[22:25], v[150:153], v[206:209], v[22:25]
	v_mfma_f32_16x16x32_bf16 v[18:21], v[158:161], v[206:209], v[18:21]
	v_mfma_f32_16x16x32_bf16 v[6:9], v[150:153], v[220:223], v[6:9]
	v_mfma_f32_16x16x32_bf16 v[2:5], v[158:161], v[220:223], v[2:5]
	s_setprio 0
	s_barrier
	s_add_i32 s66, s66, 2
	s_add_u32 s64, s64, 0x100
	s_addc_u32 s65, s65, 0
	s_cmp_gt_u32 s66, 41
	s_mov_b64 s[24:25], s[28:29]
	s_cbranch_scc0 .LBB0_313
	s_branch .Lmy_fo313_end
.Lmy_fo313_p1:
	ds_read_b128 v[168:171], v179 offset:16384
	ds_read_b128 v[172:175], v179 offset:17408
	ds_read_b128 v[180:183], v179 offset:18432
	ds_read_b128 v[198:201], v179 offset:19456
	ds_read_b128 v[202:205], v179 offset:20480
	ds_read_b128 v[206:209], v179 offset:21504
	ds_read_b128 v[210:213], v179 offset:22528
	ds_read_b128 v[220:223], v179 offset:23552
	s_waitcnt vmcnt(2)
	s_branch .Lmy_fo313_j1
.Lmy_fo313_p2:
	s_add_i32 s67, 0, 0x18000
	s_add_i32 s68, 0, 0x1c000
	v_add_u32_e32 v70, s67, v177
	v_add_u32_e32 v158, s68, v177
	ds_read_b128 v[58:61], v70
	ds_read_b128 v[62:65], v70 offset:1024
	ds_read_b128 v[66:69], v70 offset:2048
	ds_read_b128 v[70:73], v70 offset:3072
	ds_read_b128 v[146:149], v158
	ds_read_b128 v[150:153], v158 offset:1024
	ds_read_b128 v[154:157], v158 offset:2048
	ds_read_b128 v[158:161], v158 offset:3072
	ds_read_b128 v[168:171], v179 offset:32768
	ds_read_b128 v[172:175], v179 offset:33792
	ds_read_b128 v[180:183], v179 offset:34816
	ds_read_b128 v[198:201], v179 offset:35840
	ds_read_b128 v[202:205], v179 offset:36864
	ds_read_b128 v[206:209], v179 offset:37888
	ds_read_b128 v[210:213], v179 offset:38912
	ds_read_b128 v[220:223], v179 offset:39936
	s_waitcnt vmcnt(0)
	s_branch .Lmy_fo313_j2
.Lmy_fo313_p3:
	ds_read_b128 v[168:171], v179 offset:49152
	ds_read_b128 v[172:175], v179 offset:50176
	ds_read_b128 v[180:183], v179 offset:51200
	ds_read_b128 v[198:201], v179 offset:52224
	ds_read_b128 v[202:205], v179 offset:53248
	ds_read_b128 v[206:209], v179 offset:54272
	ds_read_b128 v[210:213], v179 offset:55296
	ds_read_b128 v[220:223], v179 offset:56320
	s_waitcnt vmcnt(0)
	s_branch .Lmy_fo313_j3
.Lmy_fo313_end:
	s_and_b64 vcc, exec, s[42:43]
	s_cbranch_vccz .LBB0_316
	s_barrier

; #define PG8_STAGE(bufoff, gbase, voff) do { _Pragma("unroll") for (int _i = 0; _i < 2; ++_i) \
;         __builtin_amdgcn_global_load_lds((const unsigned*)((const char*)(gbase) + (voff)[_i]), (LAS unsigned*)(lds + (bufoff) + ldsw + _i * 8192), 16, 0, 0); } while (0)
; #define PG8_LDA(dst, b, h) do { _Pragma("unroll") for (int m = 0; m < 4; ++m) _Pragma("unroll") for (int k = 0; k < 2; ++k) dst[m][k] = *(const LAS bf16x8*)(lds + PG8_SA(b, h) + aoff + m * 2048 + k * 1024); } while (0)
; #define PG8_LDB(dst, b, h) do { _Pragma("unroll") for (int n = 0; n < 2; ++n) _Pragma("unroll") for (int k = 0; k < 2; ++k) dst[n][k] = *(const LAS bf16x8*)(lds + PG8_SB(b, h) + boff + n * 2048 + k * 1024); } while (0)
; #define PG8_MMA(ai, bj, At, Bt) do { __builtin_amdgcn_s_setprio(1); _Pragma("unroll") for (int m = 0; m < 4; ++m) _Pragma("unroll") for (int n = 0; n < 2; ++n) _Pragma("unroll") for (int k = 0; k < 2; ++k) \
;         acc[ai][bj][m][n] = __builtin_amdgcn_mfma_f32_16x16x32_bf16(Bt[n][k], At[m][k], acc[ai][bj][m][n], 0, 0, 0); __builtin_amdgcn_s_setprio(0); } while (0)
; #define PG8_WAIT_V(n) asm volatile("s_waitcnt vmcnt(" #n ")" ::: "memory")
; #define PG8_BAR __builtin_amdgcn_s_barrier()
; template <class Epi, class Sched, bool ALIGN_EPI = GEMM_ALIGN, bool SP2 = GEMM_SP2>
; __device__ __forceinline__ void gemm_phase(lptr lds, const Gemm g, const Sched& S, const Epi& E) {
;     ...
;         const char* nA = has_next ? (const char*)g.A + (size_t)nxt.pm * tstepA + (size_t)nxt.acol * 2 : cA; const char* nB = has_next ? (const char*)g.Bt + (size_t)nxt.pn * tstepB : cB;
;         for (int t = 0; t < nt; t += 2) {
;             const bool last = (t == nt - 2);
;             const char* a1 = cA + (size_t)(t + 1) * kstep;
;             const char* a2 = last ? nA : cA + (size_t)(t + 2) * kstep; const char* b2 = last ? nB : cB + (size_t)(t + 2) * kstep;
;             const char* a3 = a2 + kstep; const char* b3 = b2 + kstep;
;             if constexpr (SP2) {
;             PG8_LDB(B0, 0, 0); PG8_LDB(B1, 0, 1); PG8_SCHED; PG8_LDA(At, 0, 0); PG8_STAGE(PG8_SA(1, 1), a1 + hstepA, voffA);
;             PG8_WAIT_V(8); PG8_WAIT_L(0); PG8_BAR; PG8_MMA(0, 0, At, B0); PG8_MMA(0, 1, At, B1); PG8_BAR; PG8_SCHED;
;             PG8_LDA(At, 0, 1); PG8_STAGE(PG8_SB(0, 0), b2, voffB); PG8_STAGE(PG8_SB(0, 1), b2 + hstepB, voffB); PG8_STAGE(PG8_SA(0, 0), a2, voffA);
.LBB0_2216:
	s_add_u32 s48, s30, 0xfffc0080
	s_addc_u32 s49, s31, -1
	s_add_i32 s67, 0, 0x10000
	s_cmp_eq_u32 s66, 12
	s_cselect_b32 s100, 1, 0
	s_cselect_b32 s51, s25, s49
	s_cselect_b32 s50, s34, s48
	s_cselect_b32 s49, s41, s65
	s_cselect_b32 s48, s43, s64
	s_add_i32 s70, 0, 0x14000
	v_add_u32_e32 v94, s67, v179
	v_add_u32_e32 v158, s70, v179
	ds_read_b128 v[74:77], v94
	ds_read_b128 v[82:85], v94 offset:1024
	ds_read_b128 v[90:93], v94 offset:2048
	ds_read_b128 v[94:97], v94 offset:3072
	ds_read_b128 v[146:149], v158
	ds_read_b128 v[150:153], v158 offset:1024
	ds_read_b128 v[154:157], v158 offset:2048
	ds_read_b128 v[158:161], v158 offset:3072
	v_lshl_add_u64 v[176:177], s[30:31], 0, v[164:165]
	s_add_i32 m0, s29, 0xc000
	ds_read_b128 v[168:171], v181
	ds_read_b128 v[172:175], v181 offset:1024
	ds_read_b128 v[198:201], v181 offset:2048
	ds_read_b128 v[202:205], v181 offset:3072
	ds_read_b128 v[206:209], v181 offset:4096
	ds_read_b128 v[210:213], v181 offset:5120
	ds_read_b128 v[220:223], v181 offset:6144
	ds_read_b128 v[224:227], v181 offset:7168
	global_load_lds_dwordx4 v[176:177], off
	v_lshl_add_u64 v[176:177], s[30:31], 0, v[166:167]
	s_add_i32 m0, s29, 0xe000
	s_nop 0
	global_load_lds_dwordx4 v[176:177], off
	s_waitcnt vmcnt(8)
	s_waitcnt lgkmcnt(0)
	s_barrier
	s_setprio 1
	s_waitcnt lgkmcnt(0)
	v_mfma_f32_16x16x32_bf16 v[142:145], v[74:77], v[168:171], v[142:145]
	v_mfma_f32_16x16x32_bf16 v[138:141], v[90:93], v[168:171], v[138:141]
	v_mfma_f32_16x16x32_bf16 v[126:129], v[74:77], v[198:201], v[126:129]
	v_mfma_f32_16x16x32_bf16 v[122:125], v[90:93], v[198:201], v[122:125]
	v_mfma_f32_16x16x32_bf16 v[110:113], v[74:77], v[206:209], v[110:113]
	v_mfma_f32_16x16x32_bf16 v[106:109], v[90:93], v[206:209], v[106:109]
	v_mfma_f32_16x16x32_bf16 v[86:89], v[74:77], v[220:223], v[86:89]
	v_mfma_f32_16x16x32_bf16 v[78:81], v[90:93], v[220:223], v[78:81]
	v_mfma_f32_16x16x32_bf16 v[142:145], v[82:85], v[172:175], v[142:145]
	v_mfma_f32_16x16x32_bf16 v[138:141], v[94:97], v[172:175], v[138:141]
	v_mfma_f32_16x16x32_bf16 v[126:129], v[82:85], v[202:205], v[126:129]
	v_mfma_f32_16x16x32_bf16 v[122:125], v[94:97], v[202:205], v[122:125]
	v_mfma_f32_16x16x32_bf16 v[110:113], v[82:85], v[210:213], v[110:113]
	v_mfma_f32_16x16x32_bf16 v[106:109], v[94:97], v[210:213], v[106:109]
	v_mfma_f32_16x16x32_bf16 v[86:89], v[82:85], v[224:227], v[86:89]
	v_mfma_f32_16x16x32_bf16 v[78:81], v[94:97], v[224:227], v[78:81]
	s_setprio 0
	s_setprio 1
	v_mfma_f32_16x16x32_bf16 v[134:137], v[146:149], v[168:171], v[134:137]
	v_mfma_f32_16x16x32_bf16 v[130:133], v[154:157], v[168:171], v[130:133]
	v_mfma_f32_16x16x32_bf16 v[118:121], v[146:149], v[198:201], v[118:121]
	v_mfma_f32_16x16x32_bf16 v[114:117], v[154:157], v[198:201], v[114:117]
	v_mfma_f32_16x16x32_bf16 v[102:105], v[146:149], v[206:209], v[102:105]
	v_mfma_f32_16x16x32_bf16 v[98:101], v[154:157], v[206:209], v[98:101]
	v_mfma_f32_16x16x32_bf16 v[70:73], v[146:149], v[220:223], v[70:73]
	v_mfma_f32_16x16x32_bf16 v[66:69], v[154:157], v[220:223], v[66:69]
	v_mfma_f32_16x16x32_bf16 v[134:137], v[150:153], v[172:175], v[134:137]
	v_mfma_f32_16x16x32_bf16 v[130:133], v[158:161], v[172:175], v[130:133]
	v_mfma_f32_16x16x32_bf16 v[118:121], v[150:153], v[202:205], v[118:121]
	v_mfma_f32_16x16x32_bf16 v[114:117], v[158:161], v[202:205], v[114:117]
	v_mfma_f32_16x16x32_bf16 v[102:105], v[150:153], v[210:213], v[102:105]
	v_mfma_f32_16x16x32_bf16 v[98:101], v[158:161], v[210:213], v[98:101]
	v_mfma_f32_16x16x32_bf16 v[70:73], v[150:153], v[224:227], v[70:73]
	v_mfma_f32_16x16x32_bf16 v[66:69], v[158:161], v[224:227], v[66:69]
	s_setprio 0
	s_barrier
	s_cmp_lg_u32 s100, 0
	s_cbranch_scc1 .Lmy_fo2216_p1
	s_add_i32 s67, s67, s54
	v_lshl_add_u64 v[176:177], s[48:49], 0, v[0:1]
	s_mov_b32 m0, s67
	ds_read_b128 v[168:171], v181 offset:16384
	ds_read_b128 v[172:175], v181 offset:17408
	ds_read_b128 v[198:201], v181 offset:18432
	ds_read_b128 v[202:205], v181 offset:19456
	ds_read_b128 v[206:209], v181 offset:20480
	ds_read_b128 v[210:213], v181 offset:21504
	ds_read_b128 v[220:223], v181 offset:22528
	ds_read_b128 v[224:227], v181 offset:23552
	global_load_lds_dwordx4 v[176:177], off
	s_add_i32 m0, s67, 0x2000
	s_add_u32 s68, s48, 0x40000
	v_lshl_add_u64 v[182:183], s[48:49], 0, v[162:163]
	s_addc_u32 s69, s49, 0
	s_add_i32 s67, s70, s54
	global_load_lds_dwordx4 v[182:183], off
	v_lshl_add_u64 v[214:215], s[68:69], 0, v[0:1]
	s_mov_b32 m0, s67
	v_lshl_add_u64 v[228:229], s[50:51], 0, v[162:163]
	global_load_lds_dwordx4 v[214:215], off
	v_lshl_add_u64 v[214:215], s[68:69], 0, v[162:163]
	s_add_i32 m0, s67, 0x2000
	s_nop 0
	global_load_lds_dwordx4 v[214:215], off
	v_lshl_add_u64 v[214:215], s[50:51], 0, v[0:1]
	s_mov_b32 m0, s29
	s_nop 0
	global_load_lds_dwordx4 v[214:215], off
	s_mov_b32 m0, s55
	s_nop 0
	global_load_lds_dwordx4 v[228:229], off
	s_waitcnt vmcnt(8)
; #define PG8_STAGE(bufoff, gbase, voff) do { _Pragma("unroll") for (int _i = 0; _i < 2; ++_i) \
;         __builtin_amdgcn_global_load_lds((const unsigned*)((const char*)(gbase) + (voff)[_i]), (LAS unsigned*)(lds + (bufoff) + ldsw + _i * 8192), 16, 0, 0); } while (0)
; #define PG8_LDA(dst, b, h) do { _Pragma("unroll") for (int m = 0; m < 4; ++m) _Pragma("unroll") for (int k = 0; k < 2; ++k) dst[m][k] = *(const LAS bf16x8*)(lds + PG8_SA(b, h) + aoff + m * 2048 + k * 1024); } while (0)
; #define PG8_LDB(dst, b, h) do { _Pragma("unroll") for (int n = 0; n < 2; ++n) _Pragma("unroll") for (int k = 0; k < 2; ++k) dst[n][k] = *(const LAS bf16x8*)(lds + PG8_SB(b, h) + boff + n * 2048 + k * 1024); } while (0)
; #define PG8_MMA(ai, bj, At, Bt) do { __builtin_amdgcn_s_setprio(1); _Pragma("unroll") for (int m = 0; m < 4; ++m) _Pragma("unroll") for (int n = 0; n < 2; ++n) _Pragma("unroll") for (int k = 0; k < 2; ++k) \
;         acc[ai][bj][m][n] = __builtin_amdgcn_mfma_f32_16x16x32_bf16(Bt[n][k], At[m][k], acc[ai][bj][m][n], 0, 0, 0); __builtin_amdgcn_s_setprio(0); } while (0)
; #define PG8_WAIT_V(n) asm volatile("s_waitcnt vmcnt(" #n ")" ::: "memory")
; #define PG8_WAIT_L(n) asm volatile("s_waitcnt lgkmcnt(" #n ")" ::: "memory")
; #define PG8_BAR __builtin_amdgcn_s_barrier()
; #define PG8_SCHED __builtin_amdgcn_sched_barrier(0)
; template <class Epi, class Sched, bool ALIGN_EPI = GEMM_ALIGN, bool SP2 = GEMM_SP2>
; __device__ __forceinline__ void gemm_phase(lptr lds, const Gemm g, const Sched& S, const Epi& E) {
;     ...
;             PG8_WAIT_V(8); PG8_WAIT_L(0); PG8_BAR; PG8_MMA(0, 0, At, B0); PG8_MMA(0, 1, At, B1); PG8_BAR; PG8_SCHED;
;             PG8_LDA(At, 0, 1); PG8_STAGE(PG8_SB(0, 0), b2, voffB); PG8_STAGE(PG8_SB(0, 1), b2 + hstepB, voffB); PG8_STAGE(PG8_SA(0, 0), a2, voffA);
;             PG8_WAIT_V(8); PG8_WAIT_L(0); PG8_BAR; PG8_MMA(1, 0, At, B0); PG8_MMA(1, 1, At, B1); PG8_BAR; PG8_SCHED;
;             PG8_LDB(B0, 1, 0); PG8_LDB(B1, 1, 1); PG8_SCHED; PG8_LDA(At, 1, 0); PG8_STAGE(PG8_SA(0, 1), a2 + hstepA, voffA);
;             PG8_WAIT_V(8); PG8_WAIT_L(0); PG8_BAR; PG8_MMA(0, 0, At, B0); PG8_MMA(0, 1, At, B1); PG8_BAR; PG8_SCHED;
;             PG8_LDA(At, 1, 1); PG8_STAGE(PG8_SB(1, 0), b3, voffB); PG8_STAGE(PG8_SB(1, 1), b3 + hstepB, voffB); PG8_STAGE(PG8_SA(1, 0), a3, voffA);
.Lmy_fo2216_j1:
	s_waitcnt lgkmcnt(0)
	s_barrier
	s_setprio 1
	s_waitcnt lgkmcnt(0)
	v_mfma_f32_16x16x32_bf16 v[62:65], v[74:77], v[168:171], v[62:65]
	v_mfma_f32_16x16x32_bf16 v[58:61], v[90:93], v[168:171], v[58:61]
	v_mfma_f32_16x16x32_bf16 v[46:49], v[74:77], v[198:201], v[46:49]
	v_mfma_f32_16x16x32_bf16 v[42:45], v[90:93], v[198:201], v[42:45]
	v_mfma_f32_16x16x32_bf16 v[30:33], v[74:77], v[206:209], v[30:33]
	v_mfma_f32_16x16x32_bf16 v[26:29], v[90:93], v[206:209], v[26:29]
	v_mfma_f32_16x16x32_bf16 v[14:17], v[74:77], v[220:223], v[14:17]
	v_mfma_f32_16x16x32_bf16 v[10:13], v[90:93], v[220:223], v[10:13]
	v_mfma_f32_16x16x32_bf16 v[62:65], v[82:85], v[172:175], v[62:65]
	v_mfma_f32_16x16x32_bf16 v[58:61], v[94:97], v[172:175], v[58:61]
	v_mfma_f32_16x16x32_bf16 v[46:49], v[82:85], v[202:205], v[46:49]
	v_mfma_f32_16x16x32_bf16 v[42:45], v[94:97], v[202:205], v[42:45]
	v_mfma_f32_16x16x32_bf16 v[30:33], v[82:85], v[210:213], v[30:33]
	v_mfma_f32_16x16x32_bf16 v[26:29], v[94:97], v[210:213], v[26:29]
	v_mfma_f32_16x16x32_bf16 v[14:17], v[82:85], v[224:227], v[14:17]
	v_mfma_f32_16x16x32_bf16 v[10:13], v[94:97], v[224:227], v[10:13]
	s_setprio 0
	s_setprio 1
	v_mfma_f32_16x16x32_bf16 v[54:57], v[146:149], v[168:171], v[54:57]
	v_mfma_f32_16x16x32_bf16 v[50:53], v[154:157], v[168:171], v[50:53]
	v_mfma_f32_16x16x32_bf16 v[38:41], v[146:149], v[198:201], v[38:41]
	v_mfma_f32_16x16x32_bf16 v[34:37], v[154:157], v[198:201], v[34:37]
	v_mfma_f32_16x16x32_bf16 v[22:25], v[146:149], v[206:209], v[22:25]
	v_mfma_f32_16x16x32_bf16 v[18:21], v[154:157], v[206:209], v[18:21]
	v_mfma_f32_16x16x32_bf16 v[6:9], v[146:149], v[220:223], v[6:9]
	v_mfma_f32_16x16x32_bf16 v[2:5], v[154:157], v[220:223], v[2:5]
	v_mfma_f32_16x16x32_bf16 v[54:57], v[150:153], v[172:175], v[54:57]
	v_mfma_f32_16x16x32_bf16 v[50:53], v[158:161], v[172:175], v[50:53]
	v_mfma_f32_16x16x32_bf16 v[38:41], v[150:153], v[202:205], v[38:41]
	v_mfma_f32_16x16x32_bf16 v[34:37], v[158:161], v[202:205], v[34:37]
	v_mfma_f32_16x16x32_bf16 v[22:25], v[150:153], v[210:213], v[22:25]
	v_mfma_f32_16x16x32_bf16 v[18:21], v[158:161], v[210:213], v[18:21]
	v_mfma_f32_16x16x32_bf16 v[6:9], v[150:153], v[224:227], v[6:9]
	v_mfma_f32_16x16x32_bf16 v[2:5], v[158:161], v[224:227], v[2:5]
	s_setprio 0
	s_barrier
	s_cmp_lg_u32 s100, 0
	s_cbranch_scc1 .Lmy_fo2216_p2
	s_add_i32 s67, 0, 0x18000
	s_add_i32 s68, 0, 0x1c000
	v_add_u32_e32 v94, s67, v179
	v_add_u32_e32 v158, s68, v179
	ds_read_b128 v[74:77], v94
	ds_read_b128 v[82:85], v94 offset:1024
	ds_read_b128 v[90:93], v94 offset:2048
	ds_read_b128 v[94:97], v94 offset:3072
	ds_read_b128 v[146:149], v158
	ds_read_b128 v[150:153], v158 offset:1024
	ds_read_b128 v[154:157], v158 offset:2048
	ds_read_b128 v[158:161], v158 offset:3072
	s_add_u32 s50, s50, 0x40000
	s_addc_u32 s51, s51, 0
	s_mov_b32 m0, s56
	v_lshl_add_u64 v[230:231], s[50:51], 0, v[0:1]
	ds_read_b128 v[168:171], v181 offset:32768
	ds_read_b128 v[172:175], v181 offset:33792
	ds_read_b128 v[198:201], v181 offset:34816
	ds_read_b128 v[202:205], v181 offset:35840
	ds_read_b128 v[206:209], v181 offset:36864
	ds_read_b128 v[210:213], v181 offset:37888
	ds_read_b128 v[220:223], v181 offset:38912
	ds_read_b128 v[224:227], v181 offset:39936
	global_load_lds_dwordx4 v[230:231], off
	v_lshl_add_u64 v[230:231], s[50:51], 0, v[162:163]
	s_mov_b32 m0, s57
	s_nop 0
	global_load_lds_dwordx4 v[230:231], off
	s_waitcnt vmcnt(8)
.Lmy_fo2216_j2:
	s_waitcnt lgkmcnt(0)
	s_barrier
	s_setprio 1
	s_waitcnt lgkmcnt(0)
	v_mfma_f32_16x16x32_bf16 v[142:145], v[74:77], v[168:171], v[142:145]
	v_mfma_f32_16x16x32_bf16 v[138:141], v[90:93], v[168:171], v[138:141]
	v_mfma_f32_16x16x32_bf16 v[126:129], v[74:77], v[198:201], v[126:129]
	v_mfma_f32_16x16x32_bf16 v[122:125], v[90:93], v[198:201], v[122:125]
	v_mfma_f32_16x16x32_bf16 v[110:113], v[74:77], v[206:209], v[110:113]
	v_mfma_f32_16x16x32_bf16 v[106:109], v[90:93], v[206:209], v[106:109]
	v_mfma_f32_16x16x32_bf16 v[86:89], v[74:77], v[220:223], v[86:89]
	v_mfma_f32_16x16x32_bf16 v[78:81], v[90:93], v[220:223], v[78:81]
	v_mfma_f32_16x16x32_bf16 v[142:145], v[82:85], v[172:175], v[142:145]
	v_mfma_f32_16x16x32_bf16 v[138:141], v[94:97], v[172:175], v[138:141]
	v_mfma_f32_16x16x32_bf16 v[126:129], v[82:85], v[202:205], v[126:129]
	v_mfma_f32_16x16x32_bf16 v[122:125], v[94:97], v[202:205], v[122:125]
	v_mfma_f32_16x16x32_bf16 v[110:113], v[82:85], v[210:213], v[110:113]
	v_mfma_f32_16x16x32_bf16 v[106:109], v[94:97], v[210:213], v[106:109]
	v_mfma_f32_16x16x32_bf16 v[86:89], v[82:85], v[224:227], v[86:89]
	v_mfma_f32_16x16x32_bf16 v[78:81], v[94:97], v[224:227], v[78:81]
	s_setprio 0
	s_setprio 1
	v_mfma_f32_16x16x32_bf16 v[134:137], v[146:149], v[168:171], v[134:137]
	v_mfma_f32_16x16x32_bf16 v[130:133], v[154:157], v[168:171], v[130:133]
	v_mfma_f32_16x16x32_bf16 v[118:121], v[146:149], v[198:201], v[118:121]
	v_mfma_f32_16x16x32_bf16 v[114:117], v[154:157], v[198:201], v[114:117]
	v_mfma_f32_16x16x32_bf16 v[102:105], v[146:149], v[206:209], v[102:105]
	v_mfma_f32_16x16x32_bf16 v[98:101], v[154:157], v[206:209], v[98:101]
	v_mfma_f32_16x16x32_bf16 v[70:73], v[146:149], v[220:223], v[70:73]
	v_mfma_f32_16x16x32_bf16 v[66:69], v[154:157], v[220:223], v[66:69]
	v_mfma_f32_16x16x32_bf16 v[134:137], v[150:153], v[172:175], v[134:137]
	v_mfma_f32_16x16x32_bf16 v[130:133], v[158:161], v[172:175], v[130:133]
	v_mfma_f32_16x16x32_bf16 v[118:121], v[150:153], v[202:205], v[118:121]
	v_mfma_f32_16x16x32_bf16 v[114:117], v[158:161], v[202:205], v[114:117]
	v_mfma_f32_16x16x32_bf16 v[102:105], v[150:153], v[210:213], v[102:105]
	v_mfma_f32_16x16x32_bf16 v[98:101], v[158:161], v[210:213], v[98:101]
	v_mfma_f32_16x16x32_bf16 v[70:73], v[150:153], v[224:227], v[70:73]
	v_mfma_f32_16x16x32_bf16 v[66:69], v[158:161], v[224:227], v[66:69]
	s_setprio 0
	s_barrier
; #define PG8_STAGE(bufoff, gbase, voff) do { _Pragma("unroll") for (int _i = 0; _i < 2; ++_i) \
;         __builtin_amdgcn_global_load_lds((const unsigned*)((const char*)(gbase) + (voff)[_i]), (LAS unsigned*)(lds + (bufoff) + ldsw + _i * 8192), 16, 0, 0); } while (0)
; #define PG8_LDA(dst, b, h) do { _Pragma("unroll") for (int m = 0; m < 4; ++m) _Pragma("unroll") for (int k = 0; k < 2; ++k) dst[m][k] = *(const LAS bf16x8*)(lds + PG8_SA(b, h) + aoff + m * 2048 + k * 1024); } while (0)
; #define PG8_LDB(dst, b, h) do { _Pragma("unroll") for (int n = 0; n < 2; ++n) _Pragma("unroll") for (int k = 0; k < 2; ++k) dst[n][k] = *(const LAS bf16x8*)(lds + PG8_SB(b, h) + boff + n * 2048 + k * 1024); } while (0)
; #define PG8_MMA(ai, bj, At, Bt) do { __builtin_amdgcn_s_setprio(1); _Pragma("unroll") for (int m = 0; m < 4; ++m) _Pragma("unroll") for (int n = 0; n < 2; ++n) _Pragma("unroll") for (int k = 0; k < 2; ++k) \
;         acc[ai][bj][m][n] = __builtin_amdgcn_mfma_f32_16x16x32_bf16(Bt[n][k], At[m][k], acc[ai][bj][m][n], 0, 0, 0); __builtin_amdgcn_s_setprio(0); } while (0)
; #define PG8_WAIT_V(n) asm volatile("s_waitcnt vmcnt(" #n ")" ::: "memory")
; #define PG8_WAIT_L(n) asm volatile("s_waitcnt lgkmcnt(" #n ")" ::: "memory")
; #define PG8_BAR __builtin_amdgcn_s_barrier()
; #define PG8_SCHED __builtin_amdgcn_sched_barrier(0)
; template <class Epi, class Sched, bool ALIGN_EPI = GEMM_ALIGN, bool SP2 = GEMM_SP2>
; __device__ __forceinline__ void gemm_phase(lptr lds, const Gemm g, const Sched& S, const Epi& E) {
;     ...
;             PG8_LDB(B0, 1, 0); PG8_LDB(B1, 1, 1); PG8_SCHED; PG8_LDA(At, 1, 0); PG8_STAGE(PG8_SA(0, 1), a2 + hstepA, voffA);
;             PG8_WAIT_V(8); PG8_WAIT_L(0); PG8_BAR; PG8_MMA(0, 0, At, B0); PG8_MMA(0, 1, At, B1); PG8_BAR; PG8_SCHED;
;             PG8_LDA(At, 1, 1); PG8_STAGE(PG8_SB(1, 0), b3, voffB); PG8_STAGE(PG8_SB(1, 1), b3 + hstepB, voffB); PG8_STAGE(PG8_SA(1, 0), a3, voffA);
;             PG8_WAIT_V(8); PG8_WAIT_L(0); PG8_BAR; PG8_MMA(1, 0, At, B0); PG8_MMA(1, 1, At, B1); PG8_BAR; PG8_SCHED;
	s_cmp_lg_u32 s100, 0
	s_cbranch_scc1 .Lmy_fo2216_p3
	s_add_i32 s50, s67, s54
	v_lshl_add_u64 v[176:177], v[176:177], 0, s[6:7]
	s_mov_b32 m0, s50
	ds_read_b128 v[168:171], v181 offset:49152
	ds_read_b128 v[172:175], v181 offset:50176
	ds_read_b128 v[198:201], v181 offset:51200
	ds_read_b128 v[202:205], v181 offset:52224
	ds_read_b128 v[206:209], v181 offset:53248
	ds_read_b128 v[210:213], v181 offset:54272
	ds_read_b128 v[220:223], v181 offset:55296
	ds_read_b128 v[224:227], v181 offset:56320
	global_load_lds_dwordx4 v[176:177], off
	s_add_i32 m0, s50, 0x2000
	s_add_u32 s48, s48, 0x40080
	v_lshl_add_u64 v[176:177], v[182:183], 0, s[6:7]
	s_addc_u32 s49, s49, 0
	s_add_i32 s50, s68, s54
	global_load_lds_dwordx4 v[176:177], off
	v_lshl_add_u64 v[176:177], s[48:49], 0, v[0:1]
	s_mov_b32 m0, s50
	s_nop 0
	global_load_lds_dwordx4 v[176:177], off
	v_lshl_add_u64 v[176:177], s[48:49], 0, v[162:163]
	s_add_i32 m0, s50, 0x2000
	s_nop 0
	global_load_lds_dwordx4 v[176:177], off
	v_lshl_add_u64 v[176:177], v[214:215], 0, s[6:7]
	s_mov_b32 m0, s59
	s_nop 0
	global_load_lds_dwordx4 v[176:177], off
	v_lshl_add_u64 v[176:177], v[228:229], 0, s[6:7]
	s_mov_b32 m0, s60
	s_nop 0
	global_load_lds_dwordx4 v[176:177], off
	s_waitcnt vmcnt(8)
.Lmy_fo2216_j3:
	s_waitcnt lgkmcnt(0)
	s_barrier
	s_setprio 1
	s_waitcnt lgkmcnt(0)
	v_mfma_f32_16x16x32_bf16 v[62:65], v[74:77], v[168:171], v[62:65]
	v_mfma_f32_16x16x32_bf16 v[58:61], v[90:93], v[168:171], v[58:61]
	v_mfma_f32_16x16x32_bf16 v[46:49], v[74:77], v[198:201], v[46:49]
	v_mfma_f32_16x16x32_bf16 v[42:45], v[90:93], v[198:201], v[42:45]
	v_mfma_f32_16x16x32_bf16 v[30:33], v[74:77], v[206:209], v[30:33]
	v_mfma_f32_16x16x32_bf16 v[26:29], v[90:93], v[206:209], v[26:29]
	v_mfma_f32_16x16x32_bf16 v[14:17], v[74:77], v[220:223], v[14:17]
	v_mfma_f32_16x16x32_bf16 v[10:13], v[90:93], v[220:223], v[10:13]
	v_mfma_f32_16x16x32_bf16 v[62:65], v[82:85], v[172:175], v[62:65]
	v_mfma_f32_16x16x32_bf16 v[58:61], v[94:97], v[172:175], v[58:61]
	v_mfma_f32_16x16x32_bf16 v[46:49], v[82:85], v[202:205], v[46:49]
	v_mfma_f32_16x16x32_bf16 v[42:45], v[94:97], v[202:205], v[42:45]
	v_mfma_f32_16x16x32_bf16 v[30:33], v[82:85], v[210:213], v[30:33]
	v_mfma_f32_16x16x32_bf16 v[26:29], v[94:97], v[210:213], v[26:29]
	v_mfma_f32_16x16x32_bf16 v[14:17], v[82:85], v[224:227], v[14:17]
	v_mfma_f32_16x16x32_bf16 v[10:13], v[94:97], v[224:227], v[10:13]
	s_setprio 0
	s_setprio 1
	v_mfma_f32_16x16x32_bf16 v[54:57], v[146:149], v[168:171], v[54:57]
	v_mfma_f32_16x16x32_bf16 v[50:53], v[154:157], v[168:171], v[50:53]
	v_mfma_f32_16x16x32_bf16 v[38:41], v[146:149], v[198:201], v[38:41]
	v_mfma_f32_16x16x32_bf16 v[34:37], v[154:157], v[198:201], v[34:37]
	v_mfma_f32_16x16x32_bf16 v[22:25], v[146:149], v[206:209], v[22:25]
	v_mfma_f32_16x16x32_bf16 v[18:21], v[154:157], v[206:209], v[18:21]
	v_mfma_f32_16x16x32_bf16 v[6:9], v[146:149], v[220:223], v[6:9]
	v_mfma_f32_16x16x32_bf16 v[2:5], v[154:157], v[220:223], v[2:5]
	v_mfma_f32_16x16x32_bf16 v[54:57], v[150:153], v[172:175], v[54:57]
	v_mfma_f32_16x16x32_bf16 v[50:53], v[158:161], v[172:175], v[50:53]
	v_mfma_f32_16x16x32_bf16 v[38:41], v[150:153], v[202:205], v[38:41]
	v_mfma_f32_16x16x32_bf16 v[34:37], v[158:161], v[202:205], v[34:37]
	v_mfma_f32_16x16x32_bf16 v[22:25], v[150:153], v[210:213], v[22:25]
	v_mfma_f32_16x16x32_bf16 v[18:21], v[158:161], v[210:213], v[18:21]
	v_mfma_f32_16x16x32_bf16 v[6:9], v[150:153], v[224:227], v[6:9]
	v_mfma_f32_16x16x32_bf16 v[2:5], v[158:161], v[224:227], v[2:5]
	s_setprio 0
	s_barrier
	s_add_i32 s66, s66, 2
	s_add_u32 s30, s30, 0x100
	s_addc_u32 s31, s31, 0
	s_add_u32 s64, s64, 0x100
	s_addc_u32 s65, s65, 0
	s_cmp_gt_u32 s66, 13
	s_cbranch_scc0 .LBB0_2216
	s_branch .Lmy_fo2216_end
.Lmy_fo2216_p1:
	ds_read_b128 v[168:171], v181 offset:16384
	ds_read_b128 v[172:175], v181 offset:17408
	ds_read_b128 v[198:201], v181 offset:18432
	ds_read_b128 v[202:205], v181 offset:19456
	ds_read_b128 v[206:209], v181 offset:20480
	ds_read_b128 v[210:213], v181 offset:21504
	ds_read_b128 v[220:223], v181 offset:22528
	ds_read_b128 v[224:227], v181 offset:23552
	s_waitcnt vmcnt(2)
	s_branch .Lmy_fo2216_j1
.Lmy_fo2216_p2:
	s_add_i32 s67, 0, 0x18000
	s_add_i32 s68, 0, 0x1c000
	v_add_u32_e32 v94, s67, v179
	v_add_u32_e32 v158, s68, v179
	ds_read_b128 v[74:77], v94
	ds_read_b128 v[82:85], v94 offset:1024
	ds_read_b128 v[90:93], v94 offset:2048
	ds_read_b128 v[94:97], v94 offset:3072
	ds_read_b128 v[146:149], v158
	ds_read_b128 v[150:153], v158 offset:1024
	ds_read_b128 v[154:157], v158 offset:2048
	ds_read_b128 v[158:161], v158 offset:3072
	ds_read_b128 v[168:171], v181 offset:32768
	ds_read_b128 v[172:175], v181 offset:33792
	ds_read_b128 v[198:201], v181 offset:34816
	ds_read_b128 v[202:205], v181 offset:35840
	ds_read_b128 v[206:209], v181 offset:36864
	ds_read_b128 v[210:213], v181 offset:37888
	ds_read_b128 v[220:223], v181 offset:38912
	ds_read_b128 v[224:227], v181 offset:39936
	s_waitcnt vmcnt(0)
	s_branch .Lmy_fo2216_j2
.Lmy_fo2216_p3:
	ds_read_b128 v[168:171], v181 offset:49152
	ds_read_b128 v[172:175], v181 offset:50176
	ds_read_b128 v[198:201], v181 offset:51200
	ds_read_b128 v[202:205], v181 offset:52224
	ds_read_b128 v[206:209], v181 offset:53248
	ds_read_b128 v[210:213], v181 offset:54272
	ds_read_b128 v[220:223], v181 offset:55296
	ds_read_b128 v[224:227], v181 offset:56320
	s_waitcnt vmcnt(0)
	s_branch .Lmy_fo2216_j3
.Lmy_fo2216_end:
	s_and_b64 vcc, exec, s[26:27]
	s_cbranch_vccz .LBB0_2219
	s_barrier

; #define PG8_STAGE(bufoff, gbase, voff) do { _Pragma("unroll") for (int _i = 0; _i < 2; ++_i) \
;         __builtin_amdgcn_global_load_lds((const unsigned*)((const char*)(gbase) + (voff)[_i]), (LAS unsigned*)(lds + (bufoff) + ldsw + _i * 8192), 16, 0, 0); } while (0)
; #define PG8_LDA(dst, b, h) do { _Pragma("unroll") for (int m = 0; m < 4; ++m) _Pragma("unroll") for (int k = 0; k < 2; ++k) dst[m][k] = *(const LAS bf16x8*)(lds + PG8_SA(b, h) + aoff + m * 2048 + k * 1024); } while (0)
; #define PG8_LDB(dst, b, h) do { _Pragma("unroll") for (int n = 0; n < 2; ++n) _Pragma("unroll") for (int k = 0; k < 2; ++k) dst[n][k] = *(const LAS bf16x8*)(lds + PG8_SB(b, h) + boff + n * 2048 + k * 1024); } while (0)
; #define PG8_MMA(ai, bj, At, Bt) do { __builtin_amdgcn_s_setprio(1); _Pragma("unroll") for (int m = 0; m < 4; ++m) _Pragma("unroll") for (int n = 0; n < 2; ++n) _Pragma("unroll") for (int k = 0; k < 2; ++k) \
;         acc[ai][bj][m][n] = __builtin_amdgcn_mfma_f32_16x16x32_bf16(Bt[n][k], At[m][k], acc[ai][bj][m][n], 0, 0, 0); __builtin_amdgcn_s_setprio(0); } while (0)
; #define PG8_WAIT_V(n) asm volatile("s_waitcnt vmcnt(" #n ")" ::: "memory")
; #define PG8_BAR __builtin_amdgcn_s_barrier()
; template <class Epi, class Sched, bool ALIGN_EPI = GEMM_ALIGN, bool SP2 = GEMM_SP2>
; __device__ __forceinline__ void gemm_phase(lptr lds, const Gemm g, const Sched& S, const Epi& E) {
;     ...
;         const char* nA = has_next ? (const char*)g.A + (size_t)nxt.pm * tstepA + (size_t)nxt.acol * 2 : cA; const char* nB = has_next ? (const char*)g.Bt + (size_t)nxt.pn * tstepB : cB;
;         for (int t = 0; t < nt; t += 2) {
;             const bool last = (t == nt - 2);
;             const char* a1 = cA + (size_t)(t + 1) * kstep;
;             const char* a2 = last ? nA : cA + (size_t)(t + 2) * kstep; const char* b2 = last ? nB : cB + (size_t)(t + 2) * kstep;
;             const char* a3 = a2 + kstep; const char* b3 = b2 + kstep;
;             if constexpr (SP2) {
;             PG8_LDB(B0, 0, 0); PG8_LDB(B1, 0, 1); PG8_SCHED; PG8_LDA(At, 0, 0); PG8_STAGE(PG8_SA(1, 1), a1 + hstepA, voffA);
;             PG8_WAIT_V(8); PG8_WAIT_L(0); PG8_BAR; PG8_MMA(0, 0, At, B0); PG8_MMA(0, 1, At, B1); PG8_BAR; PG8_SCHED;
;             PG8_LDA(At, 0, 1); PG8_STAGE(PG8_SB(0, 0), b2, voffB); PG8_STAGE(PG8_SB(0, 1), b2 + hstepB, voffB); PG8_STAGE(PG8_SA(0, 0), a2, voffA);
.LBB0_2418:
	s_add_u32 s2, s24, 0x100
	s_addc_u32 s3, s25, 0
	s_add_i32 s67, 0, 0x10000
	s_cmp_eq_u32 s66, 40
	s_cselect_b32 s100, 1, 0
	s_cselect_b32 s31, s45, s3
	s_cselect_b32 s30, s44, s2
	s_cselect_b32 s29, s47, s65
	s_cselect_b32 s28, s46, s49
	s_add_i32 s68, 0, 0x14000
	v_add_u32_e32 v74, s67, v248
	v_add_u32_e32 v158, s68, v248
	ds_read_b128 v[62:65], v74
	ds_read_b128 v[66:69], v74 offset:1024
	ds_read_b128 v[70:73], v74 offset:2048
	ds_read_b128 v[74:77], v74 offset:3072
	ds_read_b128 v[146:149], v158
	ds_read_b128 v[150:153], v158 offset:1024
	ds_read_b128 v[154:157], v158 offset:2048
	ds_read_b128 v[158:161], v158 offset:3072
	v_lshl_add_u64 v[182:183], s[24:25], 0, v[200:201]
	s_add_i32 m0, s53, 0xc000
	ds_read_b128 v[162:165], v250
	ds_read_b128 v[166:169], v250 offset:1024
	ds_read_b128 v[170:173], v250 offset:2048
	ds_read_b128 v[174:177], v250 offset:3072
	ds_read_b128 v[178:181], v250 offset:4096
	ds_read_b128 v[204:207], v250 offset:5120
	ds_read_b128 v[208:211], v250 offset:6144
	ds_read_b128 v[212:215], v250 offset:7168
	global_load_lds_dwordx4 v[182:183], off
	v_lshl_add_u64 v[182:183], s[24:25], 0, v[202:203]
	s_add_i32 m0, s53, 0xe000
	s_nop 0
	global_load_lds_dwordx4 v[182:183], off
	s_waitcnt vmcnt(8)
	s_waitcnt lgkmcnt(0)
	s_barrier
	s_setprio 1
	s_waitcnt lgkmcnt(0)
	v_mfma_f32_16x16x32_bf16 v[142:145], v[62:65], v[162:165], v[142:145]
	v_mfma_f32_16x16x32_bf16 v[138:141], v[70:73], v[162:165], v[138:141]
	v_mfma_f32_16x16x32_bf16 v[134:137], v[62:65], v[170:173], v[134:137]
	v_mfma_f32_16x16x32_bf16 v[122:125], v[70:73], v[170:173], v[122:125]
	v_mfma_f32_16x16x32_bf16 v[110:113], v[62:65], v[178:181], v[110:113]
	v_mfma_f32_16x16x32_bf16 v[106:109], v[70:73], v[178:181], v[106:109]
	v_mfma_f32_16x16x32_bf16 v[102:105], v[62:65], v[208:211], v[102:105]
	v_mfma_f32_16x16x32_bf16 v[90:93], v[70:73], v[208:211], v[90:93]
	v_mfma_f32_16x16x32_bf16 v[142:145], v[66:69], v[166:169], v[142:145]
	v_mfma_f32_16x16x32_bf16 v[138:141], v[74:77], v[166:169], v[138:141]
	v_mfma_f32_16x16x32_bf16 v[134:137], v[66:69], v[174:177], v[134:137]
	v_mfma_f32_16x16x32_bf16 v[122:125], v[74:77], v[174:177], v[122:125]
	v_mfma_f32_16x16x32_bf16 v[110:113], v[66:69], v[204:207], v[110:113]
	v_mfma_f32_16x16x32_bf16 v[106:109], v[74:77], v[204:207], v[106:109]
	v_mfma_f32_16x16x32_bf16 v[102:105], v[66:69], v[212:215], v[102:105]
	v_mfma_f32_16x16x32_bf16 v[90:93], v[74:77], v[212:215], v[90:93]
	s_setprio 0
	s_setprio 1
	v_mfma_f32_16x16x32_bf16 v[130:133], v[146:149], v[162:165], v[130:133]
	v_mfma_f32_16x16x32_bf16 v[126:129], v[154:157], v[162:165], v[126:129]
	v_mfma_f32_16x16x32_bf16 v[118:121], v[146:149], v[170:173], v[118:121]
	v_mfma_f32_16x16x32_bf16 v[114:117], v[154:157], v[170:173], v[114:117]
	v_mfma_f32_16x16x32_bf16 v[98:101], v[146:149], v[178:181], v[98:101]
	v_mfma_f32_16x16x32_bf16 v[94:97], v[154:157], v[178:181], v[94:97]
	v_mfma_f32_16x16x32_bf16 v[86:89], v[146:149], v[208:211], v[86:89]
	v_mfma_f32_16x16x32_bf16 v[82:85], v[154:157], v[208:211], v[82:85]
	v_mfma_f32_16x16x32_bf16 v[130:133], v[150:153], v[166:169], v[130:133]
	v_mfma_f32_16x16x32_bf16 v[126:129], v[158:161], v[166:169], v[126:129]
	v_mfma_f32_16x16x32_bf16 v[118:121], v[150:153], v[174:177], v[118:121]
	v_mfma_f32_16x16x32_bf16 v[114:117], v[158:161], v[174:177], v[114:117]
	v_mfma_f32_16x16x32_bf16 v[98:101], v[150:153], v[204:207], v[98:101]
	v_mfma_f32_16x16x32_bf16 v[94:97], v[158:161], v[204:207], v[94:97]
	v_mfma_f32_16x16x32_bf16 v[86:89], v[150:153], v[212:215], v[86:89]
	v_mfma_f32_16x16x32_bf16 v[82:85], v[158:161], v[212:215], v[82:85]
	s_setprio 0
	s_barrier
	s_cmp_lg_u32 s100, 0
	s_cbranch_scc1 .Lmy_fo2418_p1
	s_add_i32 s24, s67, s52
	v_lshl_add_u64 v[182:183], s[28:29], 0, v[0:1]
	s_mov_b32 m0, s24
	ds_read_b128 v[162:165], v250 offset:16384
	ds_read_b128 v[166:169], v250 offset:17408
	ds_read_b128 v[170:173], v250 offset:18432
	ds_read_b128 v[174:177], v250 offset:19456
	ds_read_b128 v[178:181], v250 offset:20480
	ds_read_b128 v[204:207], v250 offset:21504
	ds_read_b128 v[208:211], v250 offset:22528
	ds_read_b128 v[212:215], v250 offset:23552
	global_load_lds_dwordx4 v[182:183], off
	s_add_i32 m0, s24, 0x2000
	s_add_u32 s24, s28, 0xb0000
	v_lshl_add_u64 v[220:221], s[28:29], 0, v[198:199]
	s_addc_u32 s25, s29, 0
	s_add_i32 s67, s68, s52
	global_load_lds_dwordx4 v[220:221], off
	v_lshl_add_u64 v[222:223], s[24:25], 0, v[0:1]
	s_mov_b32 m0, s67
	v_lshl_add_u64 v[224:225], s[30:31], 0, v[198:199]
	global_load_lds_dwordx4 v[222:223], off
	v_lshl_add_u64 v[222:223], s[24:25], 0, v[198:199]
	s_add_i32 m0, s67, 0x2000
	s_nop 0
	global_load_lds_dwordx4 v[222:223], off
	v_lshl_add_u64 v[222:223], s[30:31], 0, v[0:1]
	s_mov_b32 m0, s53
	s_nop 0
	global_load_lds_dwordx4 v[222:223], off
	s_mov_b32 m0, s54
	s_nop 0
	global_load_lds_dwordx4 v[224:225], off
	s_waitcnt vmcnt(8)
; #define PG8_STAGE(bufoff, gbase, voff) do { _Pragma("unroll") for (int _i = 0; _i < 2; ++_i) \
;         __builtin_amdgcn_global_load_lds((const unsigned*)((const char*)(gbase) + (voff)[_i]), (LAS unsigned*)(lds + (bufoff) + ldsw + _i * 8192), 16, 0, 0); } while (0)
; #define PG8_LDA(dst, b, h) do { _Pragma("unroll") for (int m = 0; m < 4; ++m) _Pragma("unroll") for (int k = 0; k < 2; ++k) dst[m][k] = *(const LAS bf16x8*)(lds + PG8_SA(b, h) + aoff + m * 2048 + k * 1024); } while (0)
; #define PG8_LDB(dst, b, h) do { _Pragma("unroll") for (int n = 0; n < 2; ++n) _Pragma("unroll") for (int k = 0; k < 2; ++k) dst[n][k] = *(const LAS bf16x8*)(lds + PG8_SB(b, h) + boff + n * 2048 + k * 1024); } while (0)
; #define PG8_MMA(ai, bj, At, Bt) do { __builtin_amdgcn_s_setprio(1); _Pragma("unroll") for (int m = 0; m < 4; ++m) _Pragma("unroll") for (int n = 0; n < 2; ++n) _Pragma("unroll") for (int k = 0; k < 2; ++k) \
;         acc[ai][bj][m][n] = __builtin_amdgcn_mfma_f32_16x16x32_bf16(Bt[n][k], At[m][k], acc[ai][bj][m][n], 0, 0, 0); __builtin_amdgcn_s_setprio(0); } while (0)
; #define PG8_WAIT_V(n) asm volatile("s_waitcnt vmcnt(" #n ")" ::: "memory")
; #define PG8_WAIT_L(n) asm volatile("s_waitcnt lgkmcnt(" #n ")" ::: "memory")
; #define PG8_BAR __builtin_amdgcn_s_barrier()
; #define PG8_SCHED __builtin_amdgcn_sched_barrier(0)
; template <class Epi, class Sched, bool ALIGN_EPI = GEMM_ALIGN, bool SP2 = GEMM_SP2>
; __device__ __forceinline__ void gemm_phase(lptr lds, const Gemm g, const Sched& S, const Epi& E) {
;     ...
;             PG8_WAIT_V(8); PG8_WAIT_L(0); PG8_BAR; PG8_MMA(0, 0, At, B0); PG8_MMA(0, 1, At, B1); PG8_BAR; PG8_SCHED;
;             PG8_LDA(At, 0, 1); PG8_STAGE(PG8_SB(0, 0), b2, voffB); PG8_STAGE(PG8_SB(0, 1), b2 + hstepB, voffB); PG8_STAGE(PG8_SA(0, 0), a2, voffA);
;             PG8_WAIT_V(8); PG8_WAIT_L(0); PG8_BAR; PG8_MMA(1, 0, At, B0); PG8_MMA(1, 1, At, B1); PG8_BAR; PG8_SCHED;
;             PG8_LDB(B0, 1, 0); PG8_LDB(B1, 1, 1); PG8_SCHED; PG8_LDA(At, 1, 0); PG8_STAGE(PG8_SA(0, 1), a2 + hstepA, voffA);
;             PG8_WAIT_V(8); PG8_WAIT_L(0); PG8_BAR; PG8_MMA(0, 0, At, B0); PG8_MMA(0, 1, At, B1); PG8_BAR; PG8_SCHED;
;             PG8_LDA(At, 1, 1); PG8_STAGE(PG8_SB(1, 0), b3, voffB); PG8_STAGE(PG8_SB(1, 1), b3 + hstepB, voffB); PG8_STAGE(PG8_SA(1, 0), a3, voffA);
.Lmy_fo2418_j1:
	s_waitcnt lgkmcnt(0)
	s_barrier
	s_setprio 1
	s_waitcnt lgkmcnt(0)
	v_mfma_f32_16x16x32_bf16 v[78:81], v[62:65], v[162:165], v[78:81]
	v_mfma_f32_16x16x32_bf16 v[58:61], v[70:73], v[162:165], v[58:61]
	v_mfma_f32_16x16x32_bf16 v[54:57], v[62:65], v[170:173], v[54:57]
	v_mfma_f32_16x16x32_bf16 v[42:45], v[70:73], v[170:173], v[42:45]
	v_mfma_f32_16x16x32_bf16 v[30:33], v[62:65], v[178:181], v[30:33]
	v_mfma_f32_16x16x32_bf16 v[26:29], v[70:73], v[178:181], v[26:29]
	v_mfma_f32_16x16x32_bf16 v[22:25], v[62:65], v[208:211], v[22:25]
	v_mfma_f32_16x16x32_bf16 v[10:13], v[70:73], v[208:211], v[10:13]
	v_mfma_f32_16x16x32_bf16 v[78:81], v[66:69], v[166:169], v[78:81]
	v_mfma_f32_16x16x32_bf16 v[58:61], v[74:77], v[166:169], v[58:61]
	v_mfma_f32_16x16x32_bf16 v[54:57], v[66:69], v[174:177], v[54:57]
	v_mfma_f32_16x16x32_bf16 v[42:45], v[74:77], v[174:177], v[42:45]
	v_mfma_f32_16x16x32_bf16 v[30:33], v[66:69], v[204:207], v[30:33]
	v_mfma_f32_16x16x32_bf16 v[26:29], v[74:77], v[204:207], v[26:29]
	v_mfma_f32_16x16x32_bf16 v[22:25], v[66:69], v[212:215], v[22:25]
	v_mfma_f32_16x16x32_bf16 v[10:13], v[74:77], v[212:215], v[10:13]
	s_setprio 0
	s_setprio 1
	v_mfma_f32_16x16x32_bf16 v[50:53], v[146:149], v[162:165], v[50:53]
	v_mfma_f32_16x16x32_bf16 v[46:49], v[154:157], v[162:165], v[46:49]
	v_mfma_f32_16x16x32_bf16 v[38:41], v[146:149], v[170:173], v[38:41]
	v_mfma_f32_16x16x32_bf16 v[34:37], v[154:157], v[170:173], v[34:37]
	v_mfma_f32_16x16x32_bf16 v[18:21], v[146:149], v[178:181], v[18:21]
	v_mfma_f32_16x16x32_bf16 v[14:17], v[154:157], v[178:181], v[14:17]
	v_mfma_f32_16x16x32_bf16 v[6:9], v[146:149], v[208:211], v[6:9]
	v_mfma_f32_16x16x32_bf16 v[2:5], v[154:157], v[208:211], v[2:5]
	v_mfma_f32_16x16x32_bf16 v[50:53], v[150:153], v[166:169], v[50:53]
	v_mfma_f32_16x16x32_bf16 v[46:49], v[158:161], v[166:169], v[46:49]
	v_mfma_f32_16x16x32_bf16 v[38:41], v[150:153], v[174:177], v[38:41]
	v_mfma_f32_16x16x32_bf16 v[34:37], v[158:161], v[174:177], v[34:37]
	v_mfma_f32_16x16x32_bf16 v[18:21], v[150:153], v[204:207], v[18:21]
	v_mfma_f32_16x16x32_bf16 v[14:17], v[158:161], v[204:207], v[14:17]
	v_mfma_f32_16x16x32_bf16 v[6:9], v[150:153], v[212:215], v[6:9]
	v_mfma_f32_16x16x32_bf16 v[2:5], v[158:161], v[212:215], v[2:5]
	s_setprio 0
	s_barrier
	s_cmp_lg_u32 s100, 0
	s_cbranch_scc1 .Lmy_fo2418_p2
	s_add_i32 s67, 0, 0x18000
	s_add_i32 s68, 0, 0x1c000
	v_add_u32_e32 v74, s67, v248
	v_add_u32_e32 v158, s68, v248
	ds_read_b128 v[62:65], v74
	ds_read_b128 v[66:69], v74 offset:1024
	ds_read_b128 v[70:73], v74 offset:2048
	ds_read_b128 v[74:77], v74 offset:3072
	ds_read_b128 v[146:149], v158
	ds_read_b128 v[150:153], v158 offset:1024
	ds_read_b128 v[154:157], v158 offset:2048
	ds_read_b128 v[158:161], v158 offset:3072
	s_add_u32 s24, s30, 0xb0000
	s_addc_u32 s25, s31, 0
	s_mov_b32 m0, s55
	v_lshl_add_u64 v[226:227], s[24:25], 0, v[0:1]
	ds_read_b128 v[162:165], v250 offset:32768
	ds_read_b128 v[166:169], v250 offset:33792
	ds_read_b128 v[170:173], v250 offset:34816
	ds_read_b128 v[174:177], v250 offset:35840
	ds_read_b128 v[178:181], v250 offset:36864
	ds_read_b128 v[204:207], v250 offset:37888
	ds_read_b128 v[208:211], v250 offset:38912
	ds_read_b128 v[212:215], v250 offset:39936
	global_load_lds_dwordx4 v[226:227], off
	v_lshl_add_u64 v[226:227], s[24:25], 0, v[198:199]
	s_mov_b32 m0, s56
	s_nop 0
	global_load_lds_dwordx4 v[226:227], off
	s_waitcnt vmcnt(8)
.Lmy_fo2418_j2:
	s_waitcnt lgkmcnt(0)
	s_barrier
	s_setprio 1
	s_waitcnt lgkmcnt(0)
	v_mfma_f32_16x16x32_bf16 v[142:145], v[62:65], v[162:165], v[142:145]
	v_mfma_f32_16x16x32_bf16 v[138:141], v[70:73], v[162:165], v[138:141]
	v_mfma_f32_16x16x32_bf16 v[134:137], v[62:65], v[170:173], v[134:137]
	v_mfma_f32_16x16x32_bf16 v[122:125], v[70:73], v[170:173], v[122:125]
	v_mfma_f32_16x16x32_bf16 v[110:113], v[62:65], v[178:181], v[110:113]
	v_mfma_f32_16x16x32_bf16 v[106:109], v[70:73], v[178:181], v[106:109]
	v_mfma_f32_16x16x32_bf16 v[102:105], v[62:65], v[208:211], v[102:105]
	v_mfma_f32_16x16x32_bf16 v[90:93], v[70:73], v[208:211], v[90:93]
	v_mfma_f32_16x16x32_bf16 v[142:145], v[66:69], v[166:169], v[142:145]
	v_mfma_f32_16x16x32_bf16 v[138:141], v[74:77], v[166:169], v[138:141]
	v_mfma_f32_16x16x32_bf16 v[134:137], v[66:69], v[174:177], v[134:137]
	v_mfma_f32_16x16x32_bf16 v[122:125], v[74:77], v[174:177], v[122:125]
	v_mfma_f32_16x16x32_bf16 v[110:113], v[66:69], v[204:207], v[110:113]
	v_mfma_f32_16x16x32_bf16 v[106:109], v[74:77], v[204:207], v[106:109]
	v_mfma_f32_16x16x32_bf16 v[102:105], v[66:69], v[212:215], v[102:105]
	v_mfma_f32_16x16x32_bf16 v[90:93], v[74:77], v[212:215], v[90:93]
	s_setprio 0
	s_setprio 1
	v_mfma_f32_16x16x32_bf16 v[130:133], v[146:149], v[162:165], v[130:133]
	v_mfma_f32_16x16x32_bf16 v[126:129], v[154:157], v[162:165], v[126:129]
	v_mfma_f32_16x16x32_bf16 v[118:121], v[146:149], v[170:173], v[118:121]
	v_mfma_f32_16x16x32_bf16 v[114:117], v[154:157], v[170:173], v[114:117]
	v_mfma_f32_16x16x32_bf16 v[98:101], v[146:149], v[178:181], v[98:101]
	v_mfma_f32_16x16x32_bf16 v[94:97], v[154:157], v[178:181], v[94:97]
	v_mfma_f32_16x16x32_bf16 v[86:89], v[146:149], v[208:211], v[86:89]
	v_mfma_f32_16x16x32_bf16 v[82:85], v[154:157], v[208:211], v[82:85]
	v_mfma_f32_16x16x32_bf16 v[130:133], v[150:153], v[166:169], v[130:133]
	v_mfma_f32_16x16x32_bf16 v[126:129], v[158:161], v[166:169], v[126:129]
	v_mfma_f32_16x16x32_bf16 v[118:121], v[150:153], v[174:177], v[118:121]
	v_mfma_f32_16x16x32_bf16 v[114:117], v[158:161], v[174:177], v[114:117]
	v_mfma_f32_16x16x32_bf16 v[98:101], v[150:153], v[204:207], v[98:101]
	v_mfma_f32_16x16x32_bf16 v[94:97], v[158:161], v[204:207], v[94:97]
	v_mfma_f32_16x16x32_bf16 v[86:89], v[150:153], v[212:215], v[86:89]
	v_mfma_f32_16x16x32_bf16 v[82:85], v[158:161], v[212:215], v[82:85]
	s_setprio 0
	s_barrier
; #define PG8_STAGE(bufoff, gbase, voff) do { _Pragma("unroll") for (int _i = 0; _i < 2; ++_i) \
;         __builtin_amdgcn_global_load_lds((const unsigned*)((const char*)(gbase) + (voff)[_i]), (LAS unsigned*)(lds + (bufoff) + ldsw + _i * 8192), 16, 0, 0); } while (0)
; #define PG8_LDA(dst, b, h) do { _Pragma("unroll") for (int m = 0; m < 4; ++m) _Pragma("unroll") for (int k = 0; k < 2; ++k) dst[m][k] = *(const LAS bf16x8*)(lds + PG8_SA(b, h) + aoff + m * 2048 + k * 1024); } while (0)
; #define PG8_LDB(dst, b, h) do { _Pragma("unroll") for (int n = 0; n < 2; ++n) _Pragma("unroll") for (int k = 0; k < 2; ++k) dst[n][k] = *(const LAS bf16x8*)(lds + PG8_SB(b, h) + boff + n * 2048 + k * 1024); } while (0)
; #define PG8_MMA(ai, bj, At, Bt) do { __builtin_amdgcn_s_setprio(1); _Pragma("unroll") for (int m = 0; m < 4; ++m) _Pragma("unroll") for (int n = 0; n < 2; ++n) _Pragma("unroll") for (int k = 0; k < 2; ++k) \
;         acc[ai][bj][m][n] = __builtin_amdgcn_mfma_f32_16x16x32_bf16(Bt[n][k], At[m][k], acc[ai][bj][m][n], 0, 0, 0); __builtin_amdgcn_s_setprio(0); } while (0)
; #define PG8_WAIT_V(n) asm volatile("s_waitcnt vmcnt(" #n ")" ::: "memory")
; #define PG8_WAIT_L(n) asm volatile("s_waitcnt lgkmcnt(" #n ")" ::: "memory")
; #define PG8_BAR __builtin_amdgcn_s_barrier()
; #define PG8_SCHED __builtin_amdgcn_sched_barrier(0)
; template <class Epi, class Sched, bool ALIGN_EPI = GEMM_ALIGN, bool SP2 = GEMM_SP2>
; __device__ __forceinline__ void gemm_phase(lptr lds, const Gemm g, const Sched& S, const Epi& E) {
;     ...
;             PG8_LDB(B0, 1, 0); PG8_LDB(B1, 1, 1); PG8_SCHED; PG8_LDA(At, 1, 0); PG8_STAGE(PG8_SA(0, 1), a2 + hstepA, voffA);
;             PG8_WAIT_V(8); PG8_WAIT_L(0); PG8_BAR; PG8_MMA(0, 0, At, B0); PG8_MMA(0, 1, At, B1); PG8_BAR; PG8_SCHED;
;             PG8_LDA(At, 1, 1); PG8_STAGE(PG8_SB(1, 0), b3, voffB); PG8_STAGE(PG8_SB(1, 1), b3 + hstepB, voffB); PG8_STAGE(PG8_SA(1, 0), a3, voffA);
;             PG8_WAIT_V(8); PG8_WAIT_L(0); PG8_BAR; PG8_MMA(1, 0, At, B0); PG8_MMA(1, 1, At, B1); PG8_BAR; PG8_SCHED;
	s_cmp_lg_u32 s100, 0
	s_cbranch_scc1 .Lmy_fo2418_p3
	s_add_i32 s24, s67, s52
	v_lshl_add_u64 v[182:183], v[182:183], 0, s[6:7]
	s_mov_b32 m0, s24
	ds_read_b128 v[162:165], v250 offset:49152
	ds_read_b128 v[166:169], v250 offset:50176
	ds_read_b128 v[170:173], v250 offset:51200
	ds_read_b128 v[174:177], v250 offset:52224
	ds_read_b128 v[178:181], v250 offset:53248
	ds_read_b128 v[204:207], v250 offset:54272
	ds_read_b128 v[208:211], v250 offset:55296
	ds_read_b128 v[212:215], v250 offset:56320
	global_load_lds_dwordx4 v[182:183], off
	s_add_i32 m0, s24, 0x2000
	s_add_u32 s24, s28, 0xb0080
	v_lshl_add_u64 v[182:183], v[220:221], 0, s[6:7]
	s_addc_u32 s25, s29, 0
	s_add_i32 s28, s68, s52
	global_load_lds_dwordx4 v[182:183], off
	v_lshl_add_u64 v[182:183], s[24:25], 0, v[0:1]
	s_mov_b32 m0, s28
	s_nop 0
	global_load_lds_dwordx4 v[182:183], off
	v_lshl_add_u64 v[182:183], s[24:25], 0, v[198:199]
	s_add_i32 m0, s28, 0x2000
	s_nop 0
	global_load_lds_dwordx4 v[182:183], off
	v_lshl_add_u64 v[182:183], v[222:223], 0, s[6:7]
	s_mov_b32 m0, s58
	s_nop 0
	global_load_lds_dwordx4 v[182:183], off
	v_lshl_add_u64 v[182:183], v[224:225], 0, s[6:7]
	s_mov_b32 m0, s59
	s_nop 0
	global_load_lds_dwordx4 v[182:183], off
	s_waitcnt vmcnt(8)
.Lmy_fo2418_j3:
	s_waitcnt lgkmcnt(0)
	s_barrier
	s_setprio 1
	s_waitcnt lgkmcnt(0)
	v_mfma_f32_16x16x32_bf16 v[78:81], v[62:65], v[162:165], v[78:81]
	v_mfma_f32_16x16x32_bf16 v[58:61], v[70:73], v[162:165], v[58:61]
	v_mfma_f32_16x16x32_bf16 v[54:57], v[62:65], v[170:173], v[54:57]
	v_mfma_f32_16x16x32_bf16 v[42:45], v[70:73], v[170:173], v[42:45]
	v_mfma_f32_16x16x32_bf16 v[30:33], v[62:65], v[178:181], v[30:33]
	v_mfma_f32_16x16x32_bf16 v[26:29], v[70:73], v[178:181], v[26:29]
	v_mfma_f32_16x16x32_bf16 v[22:25], v[62:65], v[208:211], v[22:25]
	v_mfma_f32_16x16x32_bf16 v[10:13], v[70:73], v[208:211], v[10:13]
	v_mfma_f32_16x16x32_bf16 v[78:81], v[66:69], v[166:169], v[78:81]
	v_mfma_f32_16x16x32_bf16 v[58:61], v[74:77], v[166:169], v[58:61]
	v_mfma_f32_16x16x32_bf16 v[54:57], v[66:69], v[174:177], v[54:57]
	v_mfma_f32_16x16x32_bf16 v[42:45], v[74:77], v[174:177], v[42:45]
	v_mfma_f32_16x16x32_bf16 v[30:33], v[66:69], v[204:207], v[30:33]
	v_mfma_f32_16x16x32_bf16 v[26:29], v[74:77], v[204:207], v[26:29]
	v_mfma_f32_16x16x32_bf16 v[22:25], v[66:69], v[212:215], v[22:25]
	v_mfma_f32_16x16x32_bf16 v[10:13], v[74:77], v[212:215], v[10:13]
	s_setprio 0
	s_setprio 1
	v_mfma_f32_16x16x32_bf16 v[50:53], v[146:149], v[162:165], v[50:53]
	v_mfma_f32_16x16x32_bf16 v[46:49], v[154:157], v[162:165], v[46:49]
	v_mfma_f32_16x16x32_bf16 v[38:41], v[146:149], v[170:173], v[38:41]
	v_mfma_f32_16x16x32_bf16 v[34:37], v[154:157], v[170:173], v[34:37]
	v_mfma_f32_16x16x32_bf16 v[18:21], v[146:149], v[178:181], v[18:21]
	v_mfma_f32_16x16x32_bf16 v[14:17], v[154:157], v[178:181], v[14:17]
	v_mfma_f32_16x16x32_bf16 v[6:9], v[146:149], v[208:211], v[6:9]
	v_mfma_f32_16x16x32_bf16 v[2:5], v[154:157], v[208:211], v[2:5]
	v_mfma_f32_16x16x32_bf16 v[50:53], v[150:153], v[166:169], v[50:53]
	v_mfma_f32_16x16x32_bf16 v[46:49], v[158:161], v[166:169], v[46:49]
	v_mfma_f32_16x16x32_bf16 v[38:41], v[150:153], v[174:177], v[38:41]
	v_mfma_f32_16x16x32_bf16 v[34:37], v[158:161], v[174:177], v[34:37]
	v_mfma_f32_16x16x32_bf16 v[18:21], v[150:153], v[204:207], v[18:21]
	v_mfma_f32_16x16x32_bf16 v[14:17], v[158:161], v[204:207], v[14:17]
	v_mfma_f32_16x16x32_bf16 v[6:9], v[150:153], v[212:215], v[6:9]
	v_mfma_f32_16x16x32_bf16 v[2:5], v[158:161], v[212:215], v[2:5]
	s_setprio 0
	s_barrier
	s_add_i32 s66, s66, 2
	s_add_u32 s49, s49, 0x100
	s_addc_u32 s65, s65, 0
	s_cmp_gt_u32 s66, 41
	s_mov_b64 s[24:25], s[2:3]
	s_cbranch_scc0 .LBB0_2418
	s_branch .Lmy_fo2418_end
.Lmy_fo2418_p1:
	ds_read_b128 v[162:165], v250 offset:16384
	ds_read_b128 v[166:169], v250 offset:17408
	ds_read_b128 v[170:173], v250 offset:18432
	ds_read_b128 v[174:177], v250 offset:19456
	ds_read_b128 v[178:181], v250 offset:20480
	ds_read_b128 v[204:207], v250 offset:21504
	ds_read_b128 v[208:211], v250 offset:22528
	ds_read_b128 v[212:215], v250 offset:23552
	s_waitcnt vmcnt(2)
	s_branch .Lmy_fo2418_j1
.Lmy_fo2418_p2:
	s_add_i32 s67, 0, 0x18000
	s_add_i32 s68, 0, 0x1c000
	v_add_u32_e32 v74, s67, v248
	v_add_u32_e32 v158, s68, v248
	ds_read_b128 v[62:65], v74
	ds_read_b128 v[66:69], v74 offset:1024
	ds_read_b128 v[70:73], v74 offset:2048
	ds_read_b128 v[74:77], v74 offset:3072
	ds_read_b128 v[146:149], v158
	ds_read_b128 v[150:153], v158 offset:1024
	ds_read_b128 v[154:157], v158 offset:2048
	ds_read_b128 v[158:161], v158 offset:3072
	ds_read_b128 v[162:165], v250 offset:32768
	ds_read_b128 v[166:169], v250 offset:33792
	ds_read_b128 v[170:173], v250 offset:34816
	ds_read_b128 v[174:177], v250 offset:35840
	ds_read_b128 v[178:181], v250 offset:36864
	ds_read_b128 v[204:207], v250 offset:37888
	ds_read_b128 v[208:211], v250 offset:38912
	ds_read_b128 v[212:215], v250 offset:39936
	s_waitcnt vmcnt(0)
	s_branch .Lmy_fo2418_j2
.Lmy_fo2418_p3:
	ds_read_b128 v[162:165], v250 offset:49152
	ds_read_b128 v[166:169], v250 offset:50176
	ds_read_b128 v[170:173], v250 offset:51200
	ds_read_b128 v[174:177], v250 offset:52224
	ds_read_b128 v[178:181], v250 offset:53248
	ds_read_b128 v[204:207], v250 offset:54272
	ds_read_b128 v[208:211], v250 offset:55296
	ds_read_b128 v[212:215], v250 offset:56320
	s_waitcnt vmcnt(0)
	s_branch .Lmy_fo2418_j3
